# FFN-up GEMM: next tile's first three K-slabs prefetched into free LDS stages at the start of the epilogue
# speedup vs baseline: 1.0138x; 1.0138x over previous
.LBB0_2336:
	s_or_b64 exec, exec, s[0:1]
	s_mov_b64 s[10:11], s[60:61]
	s_mov_b64 s[8:9], s[60:61]
	s_mov_b64 s[2:3], s[60:61]
	s_mov_b64 s[6:7], s[60:61]
	s_mov_b64 s[0:1], s[60:61]
	s_waitcnt lgkmcnt(0)
	v_mov_b32_e32 v0, v163
	v_mov_b32_e32 v1, v228
	s_barrier
	v_readlane_b32 s4, v252, 32
	v_readfirstlane_b32 s12, v1
	s_ashr_i32 s14, s12, 3
	s_mul_hi_u32 s5, s4, 0x4200
	s_cmpk_gt_i32 s14, 0xaf
	s_mulk_i32 s4, 0x4200
	s_cbranch_scc1 .LBB0_2345
	s_load_dwordx2 s[10:11], s[10:11], 0xe8
	s_nop 0
	s_load_dwordx2 s[8:9], s[8:9], 0xe8
	s_nop 0
	s_load_dwordx2 s[2:3], s[2:3], 0xd0
	s_nop 0
	s_load_dwordx2 s[18:19], s[6:7], 0xe8
	v_ashrrev_i32_e32 v2, 1, v0
	s_waitcnt lgkmcnt(0)
	s_add_u32 s6, s10, 0x11210000
	v_and_b32_e32 v155, 0xffffff80, v2
	v_bfe_u32 v2, v0, 5, 1
	v_lshrrev_b32_e32 v3, 2, v0
	v_bfe_u32 v4, v0, 2, 2
	s_addc_u32 s7, s11, 0
	v_bitop3_b32 v3, v2, v3, 3 bitop3:0x78
	v_bitop3_b32 v2, v2, v4, 2 bitop3:0x36
	s_add_u32 s8, s8, 0x19213600
	s_load_dwordx2 s[20:21], s[0:1], 0xe8
	v_lshlrev_b32_e32 v178, 4, v2
	v_lshlrev_b32_e32 v2, 6, v0
	v_lshrrev_b32_e32 v6, 4, v0
	s_addc_u32 s9, s9, 0
	s_lshl_b64 s[10:11], s[4:5], 2
	v_and_b32_e32 v179, 0x37c0, v2
	v_xor_b32_e32 v2, v6, v0
	s_add_u32 s10, s2, s10
	v_and_b32_e32 v154, 31, v0
	v_lshlrev_b32_e32 v2, 4, v2
	s_addc_u32 s11, s3, s11
	v_or_b32_e32 v5, v155, v154
	v_lshlrev_b32_e32 v177, 4, v3
	s_lshl_b32 s0, s12, 3
	v_and_b32_e32 v2, 48, v2
	v_mov_b32_e32 v3, v129
	v_lshlrev_b32_e32 v176, 6, v5
	s_and_b32 s16, s0, 56
	v_lshl_add_u64 v[4:5], s[18:19], 0, v[2:3]
	s_mov_b64 s[0:1], 0x3210000
	v_and_b32_e32 v1, 63, v0
	v_lshl_add_u64 v[156:157], v[4:5], 0, s[0:1]
	s_waitcnt lgkmcnt(0)
	v_lshl_add_u64 v[2:3], s[20:21], 0, v[2:3]
	s_mov_b64 s[0:1], 0x2190000
	v_and_b32_e32 v174, 0xc0, v0
	v_ashrrev_i32_e32 v175, 2, v0
	v_lshl_add_u64 v[158:159], v[2:3], 0, s[0:1]
	v_lshlrev_b32_e32 v2, 4, v0
	v_cmp_gt_u32_e64 s[0:1], 32, v1
	v_cmp_lt_u32_e64 s[2:3], 31, v1
	v_lshrrev_b32_e32 v1, 3, v0
	v_bitop3_b32 v0, v6, 3, v0 bitop3:0x48
	s_lshr_b32 s15, s12, 3
	v_and_b32_e32 v181, 4, v1
	v_lshlrev_b32_e32 v0, 4, v0
	v_mov_b32_e32 v1, v129
	s_and_b32 s12, s12, 7
	v_and_b32_e32 v180, 0xfffffc00, v2
	v_lshl_add_u64 v[2:3], s[18:19], 0, v[0:1]
	s_mov_b64 s[18:19], 0x32100c0
	v_lshl_add_u32 v186, s12, 11, v175
	v_lshl_add_u64 v[0:1], s[20:21], 0, v[0:1]
	s_mov_b64 s[12:13], 0x21900c0
	v_or_b32_e32 v182, 0x18000, v179
	v_add_u32_e32 v183, 0x18000, v176
	v_or_b32_e32 v184, 0x10000, v179
	v_add_u32_e32 v185, 0x10000, v176
	v_lshl_add_u64 v[160:161], v[2:3], 0, s[18:19]
	v_lshl_add_u64 v[168:169], v[0:1], 0, s[12:13]
	s_lshl_b32 s17, s14, 5
	v_lshlrev_b32_e32 v128, 1, v154
	s_mov_b32 s101, 0
	s_branch .LBB0_2339
.LBB0_2338:
	s_or_b64 exec, exec, s[12:13]
	v_cvt_pk_bf16_f32 v143, v143, s0
	v_lshl_add_u64 v[132:133], v[132:133], 0, v[134:135]
	global_store_short v[132:133], v143, off
	v_or_b32_e32 v134, v142, v181
	v_mov_b64_e32 v[132:133], s[6:7]
	s_movk_i32 s12, 0x1600
	v_mad_i64_i32 v[132:133], s[12:13], v134, s12, v[132:133]
	v_lshl_add_u64 v[130:131], v[130:131], 1, v[132:133]
	v_mov_b32_e32 v132, v221
	v_mov_b32_e32 v133, v221
	v_mov_b32_e32 v134, v221
	v_mov_b32_e32 v135, v221
	v_lshlrev_b32_e32 v134, 2, v134
	v_xor_b32_e32 v134, 0x80, v134
	ds_bpermute_b32 v134, v134, v115
	v_lshlrev_b32_e32 v132, 2, v132
	v_lshlrev_b32_e32 v135, 2, v135
	v_xor_b32_e32 v135, 0x80, v135
	s_waitcnt lgkmcnt(0)
	v_cndmask_b32_e64 v144, v134, 0, s[0:1]
	s_waitcnt vmcnt(17)
	v_mul_f32_e32 v144, v136, v144
	v_fmac_f32_e32 v144, v137, v112
	s_waitcnt vmcnt(16)
	v_fmac_f32_e32 v144, v139, v113
	v_mul_f32_e32 v145, 0xbfb8aa3b, v144
	v_exp_f32_e32 v145, v145
	ds_bpermute_b32 v135, v135, v99
	v_xor_b32_e32 v132, 0x80, v132
	ds_bpermute_b32 v132, v132, v112
	v_add_f32_e32 v145, 1.0, v145
	v_rcp_f32_e32 v148, v145
	s_waitcnt lgkmcnt(1)
	v_cndmask_b32_e64 v146, v135, 0, s[0:1]
	s_waitcnt vmcnt(15)
	v_mul_f32_e32 v146, v138, v146
	s_waitcnt vmcnt(14)
	v_fmac_f32_e32 v146, v140, v96
	v_mul_f32_e32 v147, v144, v148
	v_mov_b32_e32 v144, v147
	v_mul_f32_e32 v145, v137, v113
	v_fmac_f32_e32 v145, v136, v112
	v_fmac_f32_e32 v145, v114, v139
	v_mul_f32_e32 v112, 0xbfb8aa3b, v145
	v_exp_f32_e32 v112, v112
	s_waitcnt vmcnt(13)
	v_fmac_f32_e32 v146, v141, v97
	v_mul_f32_e32 v144, v146, v144
	v_mov_b32_e32 v142, v221
	v_mov_b32_e32 v143, v221
	v_cvt_pk_bf16_f32 v144, v144, s0
	v_add_f32_e32 v112, 1.0, v112
	global_store_short v[130:131], v144, off
	v_rcp_f32_e32 v146, v112
	v_lshlrev_b32_e32 v133, 2, v133
	v_xor_b32_e32 v133, 0x80, v133
	v_mul_f32_e32 v147, v140, v97
	ds_bpermute_b32 v133, v133, v96
	v_fmac_f32_e32 v147, v138, v96
	v_mul_f32_e32 v144, v136, v113
	v_fmac_f32_e32 v144, v114, v137
	v_mul_f32_e32 v96, v145, v146
	v_fmac_f32_e32 v144, v115, v139
	v_mul_f32_e32 v112, 0xbfb8aa3b, v144
	v_exp_f32_e32 v145, v112
	v_fmac_f32_e32 v147, v98, v141
	s_movk_i32 s12, 0x1000
	v_mul_f32_e32 v96, v147, v96
	v_add_co_u32_e32 v112, vcc, s12, v130
	v_cvt_pk_bf16_f32 v96, v96, s0
	s_nop 0
	v_addc_co_u32_e32 v113, vcc, 0, v131, vcc
	global_store_short v[112:113], v96, off offset:1536
	v_add_f32_e32 v96, 1.0, v145
	v_rcp_f32_e32 v113, v96
	v_lshlrev_b32_e32 v142, 2, v142
	v_xor_b32_e32 v142, 0x80, v142
	ds_bpermute_b32 v142, v142, v116
	v_mul_f32_e32 v97, v138, v97
	v_fmac_f32_e32 v97, v98, v140
	v_mul_f32_e32 v112, v144, v113
	v_mul_f32_e32 v113, v115, v137
	s_waitcnt lgkmcnt(0)
	v_cndmask_b32_e64 v132, v142, v132, s[0:1]
	v_fmac_f32_e32 v97, v99, v141
	v_mov_b32_e32 v96, v112
	v_fmac_f32_e32 v113, v114, v136
	v_mul_f32_e32 v96, v97, v96
	v_fmac_f32_e32 v113, v139, v132
	v_cvt_pk_bf16_f32 v112, v96, s0
	v_mul_f32_e32 v96, 0xbfb8aa3b, v113
	v_exp_f32_e32 v114, v96
	v_add_co_u32_e32 v96, vcc, s47, v130
	v_lshlrev_b32_e32 v143, 2, v143
	s_nop 0
	v_addc_co_u32_e32 v97, vcc, 0, v131, vcc
	global_store_short v[96:97], v112, off offset:3072
	v_add_f32_e32 v96, 1.0, v114
	v_rcp_f32_e32 v112, v96
	v_mul_f32_e32 v99, v99, v140
	v_xor_b32_e32 v143, 0x80, v143
	v_fmac_f32_e32 v99, v98, v138
	ds_bpermute_b32 v143, v143, v100
	s_waitcnt lgkmcnt(0)
	v_cndmask_b32_e64 v133, v143, v133, s[0:1]
	v_mul_f32_e32 v97, v113, v112
	v_fmac_f32_e32 v99, v141, v133
	v_mov_b32_e32 v96, v97
	v_mul_f32_e32 v96, v99, v96
	s_movk_i32 s12, 0x4000
	v_cvt_pk_bf16_f32 v98, v96, s0
	v_add_co_u32_e32 v96, vcc, s12, v130
	s_nop 1
	v_addc_co_u32_e32 v97, vcc, 0, v131, vcc
	global_store_short v[96:97], v98, off offset:512
	v_mov_b32_e32 v96, v221
	s_nop 0
	v_lshlrev_b32_e32 v96, 2, v96
	v_xor_b32_e32 v96, 0x80, v96
	ds_bpermute_b32 v98, v96, v119
	v_mov_b32_e32 v96, v221
	s_nop 0
	v_lshlrev_b32_e32 v96, 2, v96
	v_xor_b32_e32 v96, 0x80, v96
	ds_bpermute_b32 v99, v96, v103
	v_mov_b32_e32 v96, v221
	s_waitcnt lgkmcnt(0)
	v_cndmask_b32_e64 v114, v99, v135, s[0:1]
	v_lshlrev_b32_e32 v96, 2, v96
	v_xor_b32_e32 v96, 0x80, v96
	ds_bpermute_b32 v112, v96, v120
	v_mov_b32_e32 v96, v221
	v_mul_f32_e32 v114, v138, v114
	v_lshlrev_b32_e32 v96, 2, v96
	v_xor_b32_e32 v96, 0x80, v96
	ds_bpermute_b32 v113, v96, v104
	v_cndmask_b32_e64 v96, v98, v134, s[0:1]
	v_mul_f32_e32 v96, v136, v96
	v_fmac_f32_e32 v96, v116, v137
	v_fmac_f32_e32 v96, v117, v139
	v_mul_f32_e32 v97, 0xbfb8aa3b, v96
	v_exp_f32_e32 v97, v97
	s_waitcnt lgkmcnt(1)
	v_cndmask_b32_e64 v115, v112, v142, s[0:1]
	s_waitcnt lgkmcnt(0)
	v_cndmask_b32_e64 v132, v113, v143, s[0:1]
	v_fmac_f32_e32 v114, v100, v140
	v_add_f32_e32 v97, 1.0, v97
	v_rcp_f32_e32 v134, v97
	v_fmac_f32_e32 v114, v101, v141
	s_mov_b32 s12, 0xb000
	v_mul_f32_e32 v133, v96, v134
	v_mov_b32_e32 v96, v133
	v_mul_f32_e32 v133, v117, v137
	v_fmac_f32_e32 v133, v116, v136
	v_mul_f32_e32 v96, v114, v96
	v_fmac_f32_e32 v133, v118, v139
	v_cvt_pk_bf16_f32 v114, v96, s0
	v_mul_f32_e32 v96, 0xbfb8aa3b, v133
	v_exp_f32_e32 v116, v96
	v_add_co_u32_e32 v96, vcc, s12, v130
	s_nop 1
	v_addc_co_u32_e32 v97, vcc, 0, v131, vcc
	global_store_short v[96:97], v114, off
	v_add_f32_e32 v96, 1.0, v116
	v_rcp_f32_e32 v114, v96
	v_mul_f32_e32 v116, v101, v140
	v_fmac_f32_e32 v116, v100, v138
	v_fmac_f32_e32 v116, v102, v141
	v_mul_f32_e32 v97, v133, v114
	v_mul_f32_e32 v114, v118, v137
	v_mov_b32_e32 v96, v97
	v_fmac_f32_e32 v114, v117, v136
	v_mul_f32_e32 v96, v116, v96
	v_fmac_f32_e32 v114, v119, v139
	v_cvt_pk_bf16_f32 v100, v96, s0
	v_mul_f32_e32 v96, 0xbfb8aa3b, v114
	v_exp_f32_e32 v116, v96
	s_mov_b32 s12, 0xc000
	v_add_co_u32_e32 v96, vcc, s12, v130
	s_nop 1
	v_addc_co_u32_e32 v97, vcc, 0, v131, vcc
	global_store_short v[96:97], v100, off offset:1536
	v_add_f32_e32 v96, 1.0, v116
	v_rcp_f32_e32 v100, v96
	v_mul_f32_e32 v116, v102, v140
	v_fmac_f32_e32 v116, v101, v138
	v_fmac_f32_e32 v116, v103, v141
	v_mul_f32_e32 v97, v114, v100
	v_mul_f32_e32 v101, v119, v137
	v_mov_b32_e32 v96, v97
	v_fmac_f32_e32 v101, v118, v136
	v_mul_f32_e32 v96, v116, v96
	v_fmac_f32_e32 v101, v139, v115
	v_cvt_pk_bf16_f32 v100, v96, s0
	v_mul_f32_e32 v96, 0xbfb8aa3b, v101
	v_exp_f32_e32 v114, v96
	s_mov_b32 s12, 0xd000
	v_add_co_u32_e32 v96, vcc, s12, v130
	v_mul_f32_e32 v103, v103, v140
	s_nop 0
	v_addc_co_u32_e32 v97, vcc, 0, v131, vcc
	global_store_short v[96:97], v100, off offset:3072
	v_add_f32_e32 v96, 1.0, v114
	v_rcp_f32_e32 v100, v96
	v_fmac_f32_e32 v103, v102, v138
	v_fmac_f32_e32 v103, v141, v132
	s_mov_b32 s12, 0xf000
	v_mul_f32_e32 v97, v101, v100
	v_mov_b32_e32 v96, v97
	v_mul_f32_e32 v96, v103, v96
	v_cvt_pk_bf16_f32 v100, v96, s0
	v_add_co_u32_e32 v96, vcc, s12, v130
	s_nop 1
	v_addc_co_u32_e32 v97, vcc, 0, v131, vcc
	global_store_short v[96:97], v100, off offset:512
	v_mov_b32_e32 v96, v221
	s_nop 0
	v_lshlrev_b32_e32 v96, 2, v96
	v_xor_b32_e32 v96, 0x80, v96
	ds_bpermute_b32 v100, v96, v123
	v_mov_b32_e32 v96, v221
	s_nop 0
	v_lshlrev_b32_e32 v96, 2, v96
	v_xor_b32_e32 v96, 0x80, v96
	ds_bpermute_b32 v101, v96, v107
	v_mov_b32_e32 v96, v221
	s_nop 0
	v_lshlrev_b32_e32 v96, 2, v96
	v_xor_b32_e32 v96, 0x80, v96
	ds_bpermute_b32 v102, v96, v124
	v_mov_b32_e32 v96, v221
	s_nop 0
	v_lshlrev_b32_e32 v96, 2, v96
	v_xor_b32_e32 v96, 0x80, v96
	ds_bpermute_b32 v103, v96, v108
	s_waitcnt lgkmcnt(3)
	v_cndmask_b32_e64 v96, v100, v98, s[0:1]
	v_mul_f32_e32 v96, v136, v96
	v_fmac_f32_e32 v96, v120, v137
	v_fmac_f32_e32 v96, v121, v139
	v_mul_f32_e32 v97, 0xbfb8aa3b, v96
	v_exp_f32_e32 v97, v97
	s_waitcnt lgkmcnt(2)
	v_cndmask_b32_e64 v98, v101, v99, s[0:1]
	s_waitcnt lgkmcnt(1)
	v_cndmask_b32_e64 v99, v102, v112, s[0:1]
	s_waitcnt lgkmcnt(0)
	v_cndmask_b32_e64 v112, v103, v113, s[0:1]
	v_add_f32_e32 v97, 1.0, v97
	v_rcp_f32_e32 v114, v97
	v_mul_f32_e32 v98, v138, v98
	v_fmac_f32_e32 v98, v104, v140
	v_fmac_f32_e32 v98, v105, v141
	v_mul_f32_e32 v113, v96, v114
	v_mov_b32_e32 v96, v113
	v_mul_f32_e32 v113, v121, v137
	v_fmac_f32_e32 v113, v120, v136
	v_mul_f32_e32 v96, v98, v96
	v_fmac_f32_e32 v113, v122, v139
	v_cvt_pk_bf16_f32 v98, v96, s0
	v_mul_f32_e32 v96, 0xbfb8aa3b, v113
	v_exp_f32_e32 v114, v96
	s_mov_b32 s12, 0x16000
	v_add_co_u32_e32 v96, vcc, s12, v130
	s_nop 1
	v_addc_co_u32_e32 v97, vcc, 0, v131, vcc
	global_store_short v[96:97], v98, off
	v_add_f32_e32 v96, 1.0, v114
	v_rcp_f32_e32 v98, v96
	v_mul_f32_e32 v114, v105, v140
	v_fmac_f32_e32 v114, v104, v138
	v_fmac_f32_e32 v114, v106, v141
	v_mul_f32_e32 v97, v113, v98
	v_mul_f32_e32 v104, v122, v137
	v_mov_b32_e32 v96, v97
	v_fmac_f32_e32 v104, v121, v136
	v_mul_f32_e32 v96, v114, v96
	v_fmac_f32_e32 v104, v123, v139
	v_cvt_pk_bf16_f32 v98, v96, s0
	v_mul_f32_e32 v96, 0xbfb8aa3b, v104
	v_exp_f32_e32 v113, v96
	s_mov_b32 s12, 0x17000
	v_add_co_u32_e32 v96, vcc, s12, v130
	s_nop 1
	v_addc_co_u32_e32 v97, vcc, 0, v131, vcc
	global_store_short v[96:97], v98, off offset:1536
	v_add_f32_e32 v96, 1.0, v113
	v_rcp_f32_e32 v98, v96
	v_mul_f32_e32 v113, v106, v140
	v_fmac_f32_e32 v113, v105, v138
	v_fmac_f32_e32 v113, v107, v141
	v_mul_f32_e32 v97, v104, v98
	v_mov_b32_e32 v96, v97
	v_mul_f32_e32 v104, v123, v137
	v_fmac_f32_e32 v104, v122, v136
	v_mul_f32_e32 v96, v113, v96
	v_fmac_f32_e32 v104, v139, v99
	v_cvt_pk_bf16_f32 v98, v96, s0
	v_mul_f32_e32 v96, 0xbfb8aa3b, v104
	v_exp_f32_e32 v99, v96
	s_mov_b32 s12, 0x18000
	v_add_co_u32_e32 v96, vcc, s12, v130
	s_nop 1
	v_addc_co_u32_e32 v97, vcc, 0, v131, vcc
	global_store_short v[96:97], v98, off offset:3072
	v_add_f32_e32 v96, 1.0, v99
	v_rcp_f32_e32 v98, v96
	v_mul_f32_e32 v99, v107, v140
	v_fmac_f32_e32 v99, v106, v138
	v_fmac_f32_e32 v99, v141, v112
	v_mul_f32_e32 v97, v104, v98
	v_mov_b32_e32 v96, v97
	v_mul_f32_e32 v96, v99, v96
	s_mov_b32 s12, 0x1a000
	v_cvt_pk_bf16_f32 v98, v96, s0
	v_add_co_u32_e32 v96, vcc, s12, v130
	s_nop 1
	v_addc_co_u32_e32 v97, vcc, 0, v131, vcc
	global_store_short v[96:97], v98, off offset:512
	v_mov_b32_e32 v96, v221
	s_nop 0
	v_lshlrev_b32_e32 v96, 2, v96
	v_xor_b32_e32 v96, 0x80, v96
	ds_bpermute_b32 v98, v96, v127
	v_mov_b32_e32 v96, v221
	s_nop 0
	v_lshlrev_b32_e32 v96, 2, v96
	v_xor_b32_e32 v96, 0x80, v96
	ds_bpermute_b32 v99, v96, v111
	v_mov_b32_e32 v96, v221
	s_nop 0
	v_lshlrev_b32_e32 v96, 2, v96
	v_xor_b32_e32 v96, 0x80, v96
	ds_bpermute_b32 v104, v96, v80
	v_mov_b32_e32 v96, v221
	s_nop 0
	v_lshlrev_b32_e32 v96, 2, v96
	v_xor_b32_e32 v96, 0x80, v96
	ds_bpermute_b32 v105, v96, v64
	s_waitcnt lgkmcnt(3)
	v_cndmask_b32_e64 v96, v98, v100, s[0:1]
	v_mul_f32_e32 v96, v136, v96
	v_fmac_f32_e32 v96, v124, v137
	v_fmac_f32_e32 v96, v125, v139
	v_mul_f32_e32 v97, 0xbfb8aa3b, v96
	v_exp_f32_e32 v97, v97
	s_waitcnt lgkmcnt(2)
	v_cndmask_b32_e64 v100, v99, v101, s[0:1]
	s_waitcnt lgkmcnt(1)
	v_cndmask_b32_e64 v101, v104, v102, s[0:1]
	s_waitcnt lgkmcnt(0)
	v_cndmask_b32_e64 v102, v105, v103, s[0:1]
	v_add_f32_e32 v97, 1.0, v97
	v_rcp_f32_e32 v106, v97
	v_mul_f32_e32 v100, v138, v100
	v_fmac_f32_e32 v100, v108, v140
	v_fmac_f32_e32 v100, v109, v141
	v_mul_f32_e32 v103, v96, v106
	v_mov_b32_e32 v96, v103
	v_mul_f32_e32 v103, v125, v137
	v_fmac_f32_e32 v103, v124, v136
	v_mul_f32_e32 v96, v100, v96
	v_fmac_f32_e32 v103, v126, v139
	v_cvt_pk_bf16_f32 v100, v96, s0
	v_mul_f32_e32 v96, 0xbfb8aa3b, v103
	v_exp_f32_e32 v106, v96
	s_mov_b32 s12, 0x21000
	v_add_co_u32_e32 v96, vcc, s12, v130
	s_nop 1
	v_addc_co_u32_e32 v97, vcc, 0, v131, vcc
	global_store_short v[96:97], v100, off
	v_add_f32_e32 v96, 1.0, v106
	v_rcp_f32_e32 v100, v96
	v_mul_f32_e32 v106, v109, v140
	v_fmac_f32_e32 v106, v108, v138
	v_fmac_f32_e32 v106, v110, v141
	v_mul_f32_e32 v97, v103, v100
	v_mov_b32_e32 v96, v97
	v_mul_f32_e32 v103, v126, v137
	v_fmac_f32_e32 v103, v125, v136
	v_mul_f32_e32 v96, v106, v96
	v_fmac_f32_e32 v103, v127, v139
	v_cvt_pk_bf16_f32 v100, v96, s0
	v_mul_f32_e32 v96, 0xbfb8aa3b, v103
	v_exp_f32_e32 v106, v96
	s_mov_b32 s12, 0x22000
	v_add_co_u32_e32 v96, vcc, s12, v130
	s_nop 1
	v_addc_co_u32_e32 v97, vcc, 0, v131, vcc
	global_store_short v[96:97], v100, off offset:1536
	v_add_f32_e32 v96, 1.0, v106
	v_rcp_f32_e32 v100, v96
	v_mul_f32_e32 v106, v110, v140
	v_fmac_f32_e32 v106, v109, v138
	v_fmac_f32_e32 v106, v111, v141
	v_mul_f32_e32 v97, v103, v100
	v_mov_b32_e32 v96, v97
	v_mul_f32_e32 v103, v127, v137
	v_fmac_f32_e32 v103, v126, v136
	v_mul_f32_e32 v96, v106, v96
	v_fmac_f32_e32 v103, v139, v101
	v_cvt_pk_bf16_f32 v100, v96, s0
	v_mul_f32_e32 v96, 0xbfb8aa3b, v103
	v_exp_f32_e32 v101, v96
	s_mov_b32 s12, 0x23000
	v_add_co_u32_e32 v96, vcc, s12, v130
	s_nop 1
	v_addc_co_u32_e32 v97, vcc, 0, v131, vcc
	global_store_short v[96:97], v100, off offset:3072
	v_add_f32_e32 v96, 1.0, v101
	v_rcp_f32_e32 v100, v96
	v_mul_f32_e32 v101, v111, v140
	v_fmac_f32_e32 v101, v110, v138
	v_fmac_f32_e32 v101, v141, v102
	v_mul_f32_e32 v97, v103, v100
	v_mov_b32_e32 v96, v97
	v_mul_f32_e32 v96, v101, v96
	s_mov_b32 s12, 0x25000
	v_cvt_pk_bf16_f32 v100, v96, s0
	v_add_co_u32_e32 v96, vcc, s12, v130
	s_nop 1
	v_addc_co_u32_e32 v97, vcc, 0, v131, vcc
	global_store_short v[96:97], v100, off offset:512
	v_mov_b32_e32 v96, v221
	s_nop 0
	v_lshlrev_b32_e32 v96, 2, v96
	v_xor_b32_e32 v96, 0x80, v96
	ds_bpermute_b32 v100, v96, v83
	v_mov_b32_e32 v96, v221
	s_nop 0
	v_lshlrev_b32_e32 v96, 2, v96
	v_xor_b32_e32 v96, 0x80, v96
	ds_bpermute_b32 v101, v96, v67
	v_mov_b32_e32 v96, v221
	s_nop 0
	v_lshlrev_b32_e32 v96, 2, v96
	v_xor_b32_e32 v96, 0x80, v96
	ds_bpermute_b32 v102, v96, v84
	v_mov_b32_e32 v96, v221
	s_nop 0
	v_lshlrev_b32_e32 v96, 2, v96
	v_xor_b32_e32 v96, 0x80, v96
	ds_bpermute_b32 v103, v96, v68
	s_waitcnt lgkmcnt(3)
	v_cndmask_b32_e64 v96, v100, v98, s[0:1]
	v_mul_f32_e32 v96, v136, v96
	v_fmac_f32_e32 v96, v80, v137
	v_fmac_f32_e32 v96, v81, v139
	v_mul_f32_e32 v97, 0xbfb8aa3b, v96
	v_exp_f32_e32 v97, v97
	s_waitcnt lgkmcnt(2)
	v_cndmask_b32_e64 v98, v101, v99, s[0:1]
	s_waitcnt lgkmcnt(1)
	v_cndmask_b32_e64 v99, v102, v104, s[0:1]
	s_waitcnt lgkmcnt(0)
	v_cndmask_b32_e64 v104, v103, v105, s[0:1]
	v_add_f32_e32 v97, 1.0, v97
	v_rcp_f32_e32 v106, v97
	v_mul_f32_e32 v98, v138, v98
	v_fmac_f32_e32 v98, v64, v140
	v_fmac_f32_e32 v98, v65, v141
	v_mul_f32_e32 v105, v96, v106
	v_mov_b32_e32 v96, v105
	v_mul_f32_e32 v105, v81, v137
	v_fmac_f32_e32 v105, v80, v136
	v_fmac_f32_e32 v105, v82, v139
	v_mul_f32_e32 v80, 0xbfb8aa3b, v105
	v_exp_f32_e32 v80, v80
	v_mul_f32_e32 v96, v98, v96
	s_mov_b32 s12, 0x2c000
	v_cvt_pk_bf16_f32 v98, v96, s0
	v_add_co_u32_e32 v96, vcc, s12, v130
	v_add_f32_e32 v80, 1.0, v80
	s_nop 0
	v_addc_co_u32_e32 v97, vcc, 0, v131, vcc
	global_store_short v[96:97], v98, off
	v_rcp_f32_e32 v97, v80
	v_mul_f32_e32 v98, v65, v140
	v_fmac_f32_e32 v98, v64, v138
	v_fmac_f32_e32 v98, v66, v141
	v_mul_f32_e32 v96, v82, v137
	v_fmac_f32_e32 v96, v81, v136
	v_mul_f32_e32 v64, v105, v97
	v_fmac_f32_e32 v96, v83, v139
	v_mul_f32_e32 v80, 0xbfb8aa3b, v96
	v_exp_f32_e32 v97, v80
	s_mov_b32 s12, 0x2d000
	v_mul_f32_e32 v64, v98, v64
	v_add_co_u32_e32 v80, vcc, s12, v130
	v_cvt_pk_bf16_f32 v64, v64, s0
	s_nop 0
	v_addc_co_u32_e32 v81, vcc, 0, v131, vcc
	global_store_short v[80:81], v64, off offset:1536
	v_add_f32_e32 v64, 1.0, v97
	v_rcp_f32_e32 v81, v64
	v_mul_f32_e32 v97, v66, v140
	v_fmac_f32_e32 v97, v65, v138
	v_fmac_f32_e32 v97, v67, v141
	v_mul_f32_e32 v65, v96, v81
	v_mul_f32_e32 v81, v83, v137
	v_mov_b32_e32 v64, v65
	v_fmac_f32_e32 v81, v82, v136
	v_mul_f32_e32 v64, v97, v64
	v_fmac_f32_e32 v81, v139, v99
	v_cvt_pk_bf16_f32 v80, v64, s0
	v_mul_f32_e32 v64, 0xbfb8aa3b, v81
	v_exp_f32_e32 v82, v64
	s_mov_b32 s12, 0x2e000
	v_add_co_u32_e32 v64, vcc, s12, v130
	v_mul_f32_e32 v67, v67, v140
	s_nop 0
	v_addc_co_u32_e32 v65, vcc, 0, v131, vcc
	global_store_short v[64:65], v80, off offset:3072
	v_add_f32_e32 v64, 1.0, v82
	v_rcp_f32_e32 v80, v64
	v_fmac_f32_e32 v67, v66, v138
	v_fmac_f32_e32 v67, v141, v104
	s_mov_b32 s12, 0x30000
	v_mul_f32_e32 v65, v81, v80
	v_mov_b32_e32 v64, v65
	v_mul_f32_e32 v64, v67, v64
	v_cvt_pk_bf16_f32 v66, v64, s0
	v_add_co_u32_e32 v64, vcc, s12, v130
	s_nop 1
	v_addc_co_u32_e32 v65, vcc, 0, v131, vcc
	global_store_short v[64:65], v66, off offset:512
	v_mov_b32_e32 v64, v221
	s_nop 0
	v_lshlrev_b32_e32 v64, 2, v64
	v_xor_b32_e32 v64, 0x80, v64
	ds_bpermute_b32 v66, v64, v87
	v_mov_b32_e32 v64, v221
	s_nop 0
	v_lshlrev_b32_e32 v64, 2, v64
	v_xor_b32_e32 v64, 0x80, v64
	ds_bpermute_b32 v67, v64, v71
	v_mov_b32_e32 v64, v221
	s_waitcnt lgkmcnt(0)
	v_cndmask_b32_e64 v82, v67, v101, s[0:1]
	v_lshlrev_b32_e32 v64, 2, v64
	v_xor_b32_e32 v64, 0x80, v64
	ds_bpermute_b32 v80, v64, v88
	v_mov_b32_e32 v64, v221
	v_mul_f32_e32 v82, v138, v82
	v_lshlrev_b32_e32 v64, 2, v64
	v_xor_b32_e32 v64, 0x80, v64
	ds_bpermute_b32 v81, v64, v72
	v_cndmask_b32_e64 v64, v66, v100, s[0:1]
	v_mul_f32_e32 v64, v136, v64
	v_fmac_f32_e32 v64, v84, v137
	v_fmac_f32_e32 v64, v85, v139
	v_mul_f32_e32 v65, 0xbfb8aa3b, v64
	v_exp_f32_e32 v65, v65
	v_fmac_f32_e32 v82, v68, v140
	v_fmac_f32_e32 v82, v69, v141
	s_waitcnt lgkmcnt(1)
	v_cndmask_b32_e64 v83, v80, v102, s[0:1]
	v_add_f32_e32 v65, 1.0, v65
	v_rcp_f32_e32 v98, v65
	s_mov_b32 s12, 0x37000
	s_waitcnt lgkmcnt(0)
	v_cndmask_b32_e64 v96, v81, v103, s[0:1]
	v_mul_f32_e32 v97, v64, v98
	v_mov_b32_e32 v64, v97
	v_mul_f32_e32 v97, v85, v137
	v_fmac_f32_e32 v97, v84, v136
	v_mul_f32_e32 v64, v82, v64
	v_fmac_f32_e32 v97, v86, v139
	v_cvt_pk_bf16_f32 v82, v64, s0
	v_mul_f32_e32 v64, 0xbfb8aa3b, v97
	v_exp_f32_e32 v84, v64
	v_add_co_u32_e32 v64, vcc, s12, v130
	s_nop 1
	v_addc_co_u32_e32 v65, vcc, 0, v131, vcc
	global_store_short v[64:65], v82, off
	v_add_f32_e32 v64, 1.0, v84
	v_rcp_f32_e32 v82, v64
	v_mul_f32_e32 v84, v69, v140
	v_fmac_f32_e32 v84, v68, v138
	v_fmac_f32_e32 v84, v70, v141
	v_mul_f32_e32 v65, v97, v82
	v_mul_f32_e32 v82, v86, v137
	v_mov_b32_e32 v64, v65
	v_fmac_f32_e32 v82, v85, v136
	v_mul_f32_e32 v64, v84, v64
	v_fmac_f32_e32 v82, v87, v139
	v_cvt_pk_bf16_f32 v68, v64, s0
	v_mul_f32_e32 v64, 0xbfb8aa3b, v82
	v_exp_f32_e32 v84, v64
	s_mov_b32 s12, 0x38000
	v_add_co_u32_e32 v64, vcc, s12, v130
	s_nop 1
	v_addc_co_u32_e32 v65, vcc, 0, v131, vcc
	global_store_short v[64:65], v68, off offset:1536
	v_add_f32_e32 v64, 1.0, v84
	v_rcp_f32_e32 v68, v64
	v_mul_f32_e32 v84, v70, v140
	v_fmac_f32_e32 v84, v69, v138
	v_fmac_f32_e32 v84, v71, v141
	v_mul_f32_e32 v65, v82, v68
	v_mul_f32_e32 v69, v87, v137
	v_mov_b32_e32 v64, v65
	v_fmac_f32_e32 v69, v86, v136
	v_mul_f32_e32 v64, v84, v64
	v_fmac_f32_e32 v69, v139, v83
	v_cvt_pk_bf16_f32 v68, v64, s0
	v_mul_f32_e32 v64, 0xbfb8aa3b, v69
	v_exp_f32_e32 v82, v64
	s_mov_b32 s12, 0x39000
	v_add_co_u32_e32 v64, vcc, s12, v130
	v_mul_f32_e32 v71, v71, v140
	s_nop 0
	v_addc_co_u32_e32 v65, vcc, 0, v131, vcc
	global_store_short v[64:65], v68, off offset:3072
	v_add_f32_e32 v64, 1.0, v82
	v_rcp_f32_e32 v68, v64
	v_fmac_f32_e32 v71, v70, v138
	v_fmac_f32_e32 v71, v141, v96
	s_mov_b32 s12, 0x3b000
	v_mul_f32_e32 v65, v69, v68
	v_mov_b32_e32 v64, v65
	v_mul_f32_e32 v64, v71, v64
	v_cvt_pk_bf16_f32 v68, v64, s0
	v_add_co_u32_e32 v64, vcc, s12, v130
	s_nop 1
	v_addc_co_u32_e32 v65, vcc, 0, v131, vcc
	global_store_short v[64:65], v68, off offset:512
	v_mov_b32_e32 v64, v221
	s_nop 0
	v_lshlrev_b32_e32 v64, 2, v64
	v_xor_b32_e32 v64, 0x80, v64
	ds_bpermute_b32 v68, v64, v91
	v_mov_b32_e32 v64, v221
	s_nop 0
	v_lshlrev_b32_e32 v64, 2, v64
	v_xor_b32_e32 v64, 0x80, v64
	ds_bpermute_b32 v69, v64, v75
	v_mov_b32_e32 v64, v221
	s_nop 0
	v_lshlrev_b32_e32 v64, 2, v64
	v_xor_b32_e32 v64, 0x80, v64
	ds_bpermute_b32 v70, v64, v92
	v_mov_b32_e32 v64, v221
	s_nop 0
	v_lshlrev_b32_e32 v64, 2, v64
	v_xor_b32_e32 v64, 0x80, v64
	ds_bpermute_b32 v71, v64, v76
	s_waitcnt lgkmcnt(3)
	v_cndmask_b32_e64 v64, v68, v66, s[0:1]
	v_mul_f32_e32 v64, v136, v64
	v_fmac_f32_e32 v64, v88, v137
	v_fmac_f32_e32 v64, v89, v139
	v_mul_f32_e32 v65, 0xbfb8aa3b, v64
	v_exp_f32_e32 v65, v65
	s_waitcnt lgkmcnt(2)
	v_cndmask_b32_e64 v66, v69, v67, s[0:1]
	s_waitcnt lgkmcnt(1)
	v_cndmask_b32_e64 v67, v70, v80, s[0:1]
	s_waitcnt lgkmcnt(0)
	v_cndmask_b32_e64 v80, v71, v81, s[0:1]
	v_add_f32_e32 v65, 1.0, v65
	v_rcp_f32_e32 v82, v65
	v_mul_f32_e32 v66, v138, v66
	v_fmac_f32_e32 v66, v72, v140
	v_fmac_f32_e32 v66, v73, v141
	v_mul_f32_e32 v81, v64, v82
	v_mov_b32_e32 v64, v81
	v_mul_f32_e32 v81, v89, v137
	v_fmac_f32_e32 v81, v88, v136
	v_mul_f32_e32 v64, v66, v64
	v_fmac_f32_e32 v81, v90, v139
	v_cvt_pk_bf16_f32 v66, v64, s0
	v_mul_f32_e32 v64, 0xbfb8aa3b, v81
	v_exp_f32_e32 v82, v64
	s_mov_b32 s12, 0x42000
	v_add_co_u32_e32 v64, vcc, s12, v130
	s_nop 1
	v_addc_co_u32_e32 v65, vcc, 0, v131, vcc
	global_store_short v[64:65], v66, off
	v_add_f32_e32 v64, 1.0, v82
	v_rcp_f32_e32 v66, v64
	v_mul_f32_e32 v82, v73, v140
	v_fmac_f32_e32 v82, v72, v138
	v_fmac_f32_e32 v82, v74, v141
	v_mul_f32_e32 v65, v81, v66
	v_mul_f32_e32 v72, v90, v137
	v_mov_b32_e32 v64, v65
	v_fmac_f32_e32 v72, v89, v136
	v_mul_f32_e32 v64, v82, v64
	v_fmac_f32_e32 v72, v91, v139
	v_cvt_pk_bf16_f32 v66, v64, s0
	v_mul_f32_e32 v64, 0xbfb8aa3b, v72
	v_exp_f32_e32 v81, v64
	s_mov_b32 s12, 0x43000
	v_add_co_u32_e32 v64, vcc, s12, v130
	s_nop 1
	v_addc_co_u32_e32 v65, vcc, 0, v131, vcc
	global_store_short v[64:65], v66, off offset:1536
	v_add_f32_e32 v64, 1.0, v81
	v_rcp_f32_e32 v66, v64
	v_mul_f32_e32 v81, v74, v140
	v_fmac_f32_e32 v81, v73, v138
	v_fmac_f32_e32 v81, v75, v141
	v_mul_f32_e32 v65, v72, v66
	v_mov_b32_e32 v64, v65
	v_mul_f32_e32 v72, v91, v137
	v_fmac_f32_e32 v72, v90, v136
	v_mul_f32_e32 v64, v81, v64
	v_fmac_f32_e32 v72, v139, v67
	v_cvt_pk_bf16_f32 v66, v64, s0
	v_mul_f32_e32 v64, 0xbfb8aa3b, v72
	v_exp_f32_e32 v67, v64
	s_mov_b32 s12, 0x44000
	v_add_co_u32_e32 v64, vcc, s12, v130
	s_nop 1
	v_addc_co_u32_e32 v65, vcc, 0, v131, vcc
	global_store_short v[64:65], v66, off offset:3072
	v_add_f32_e32 v64, 1.0, v67
	v_rcp_f32_e32 v66, v64
	v_mul_f32_e32 v67, v75, v140
	v_fmac_f32_e32 v67, v74, v138
	v_fmac_f32_e32 v67, v141, v80
	v_mul_f32_e32 v65, v72, v66
	v_mov_b32_e32 v64, v65
	v_mul_f32_e32 v64, v67, v64
	s_mov_b32 s12, 0x46000
	v_cvt_pk_bf16_f32 v66, v64, s0
	v_add_co_u32_e32 v64, vcc, s12, v130
	s_nop 1
	v_addc_co_u32_e32 v65, vcc, 0, v131, vcc
	global_store_short v[64:65], v66, off offset:512
	v_mov_b32_e32 v64, v221
	s_nop 0
	v_lshlrev_b32_e32 v64, 2, v64
	v_xor_b32_e32 v64, 0x80, v64
	ds_bpermute_b32 v66, v64, v95
	v_mov_b32_e32 v64, v221
	s_nop 0
	v_lshlrev_b32_e32 v64, 2, v64
	v_xor_b32_e32 v64, 0x80, v64
	ds_bpermute_b32 v67, v64, v79
	v_mov_b32_e32 v64, v221
	s_nop 0
	v_lshlrev_b32_e32 v64, 2, v64
	v_xor_b32_e32 v64, 0x80, v64
	ds_bpermute_b32 v72, v64, v48
	v_mov_b32_e32 v64, v221
	s_nop 0
	v_lshlrev_b32_e32 v64, 2, v64
	v_xor_b32_e32 v64, 0x80, v64
	ds_bpermute_b32 v73, v64, v32
	s_waitcnt lgkmcnt(3)
	v_cndmask_b32_e64 v64, v66, v68, s[0:1]
	v_mul_f32_e32 v64, v136, v64
	v_fmac_f32_e32 v64, v92, v137
	v_fmac_f32_e32 v64, v93, v139
	v_mul_f32_e32 v65, 0xbfb8aa3b, v64
	v_exp_f32_e32 v65, v65
	s_waitcnt lgkmcnt(2)
	v_cndmask_b32_e64 v68, v67, v69, s[0:1]
	s_waitcnt lgkmcnt(1)
	v_cndmask_b32_e64 v69, v72, v70, s[0:1]
	s_waitcnt lgkmcnt(0)
	v_cndmask_b32_e64 v70, v73, v71, s[0:1]
	v_add_f32_e32 v65, 1.0, v65
	v_rcp_f32_e32 v74, v65
	v_mul_f32_e32 v68, v138, v68
	v_fmac_f32_e32 v68, v76, v140
	v_fmac_f32_e32 v68, v77, v141
	v_mul_f32_e32 v71, v64, v74
	v_mov_b32_e32 v64, v71
	v_mul_f32_e32 v71, v93, v137
	v_fmac_f32_e32 v71, v92, v136
	v_mul_f32_e32 v64, v68, v64
	v_fmac_f32_e32 v71, v94, v139
	v_cvt_pk_bf16_f32 v68, v64, s0
	v_mul_f32_e32 v64, 0xbfb8aa3b, v71
	v_exp_f32_e32 v74, v64
	s_mov_b32 s12, 0x4d000
	v_add_co_u32_e32 v64, vcc, s12, v130
	s_nop 1
	v_addc_co_u32_e32 v65, vcc, 0, v131, vcc
	global_store_short v[64:65], v68, off
	v_add_f32_e32 v64, 1.0, v74
	v_rcp_f32_e32 v68, v64
	v_mul_f32_e32 v74, v77, v140
	v_fmac_f32_e32 v74, v76, v138
	v_fmac_f32_e32 v74, v78, v141
	v_mul_f32_e32 v65, v71, v68
	v_mov_b32_e32 v64, v65
	v_mul_f32_e32 v71, v94, v137
	v_fmac_f32_e32 v71, v93, v136
	v_mul_f32_e32 v64, v74, v64
	v_fmac_f32_e32 v71, v95, v139
	v_cvt_pk_bf16_f32 v68, v64, s0
	v_mul_f32_e32 v64, 0xbfb8aa3b, v71
	v_exp_f32_e32 v74, v64
	s_mov_b32 s12, 0x4e000
	v_add_co_u32_e32 v64, vcc, s12, v130
	s_nop 1
	v_addc_co_u32_e32 v65, vcc, 0, v131, vcc
	global_store_short v[64:65], v68, off offset:1536
	v_add_f32_e32 v64, 1.0, v74
	v_rcp_f32_e32 v68, v64
	v_mul_f32_e32 v74, v78, v140
	v_fmac_f32_e32 v74, v77, v138
	v_fmac_f32_e32 v74, v79, v141
	v_mul_f32_e32 v65, v71, v68
	v_mov_b32_e32 v64, v65
	v_mul_f32_e32 v71, v95, v137
	v_fmac_f32_e32 v71, v94, v136
	v_mul_f32_e32 v64, v74, v64
	v_fmac_f32_e32 v71, v139, v69
	v_cvt_pk_bf16_f32 v68, v64, s0
	v_mul_f32_e32 v64, 0xbfb8aa3b, v71
	v_exp_f32_e32 v69, v64
	s_mov_b32 s12, 0x4f000
	v_add_co_u32_e32 v64, vcc, s12, v130
	s_nop 1
	v_addc_co_u32_e32 v65, vcc, 0, v131, vcc
	global_store_short v[64:65], v68, off offset:3072
	v_add_f32_e32 v64, 1.0, v69
	v_rcp_f32_e32 v68, v64
	v_mul_f32_e32 v69, v79, v140
	v_fmac_f32_e32 v69, v78, v138
	v_fmac_f32_e32 v69, v141, v70
	v_mul_f32_e32 v65, v71, v68
	v_mov_b32_e32 v64, v65
	v_mul_f32_e32 v64, v69, v64
	s_mov_b32 s12, 0x51000
	v_cvt_pk_bf16_f32 v68, v64, s0
	v_add_co_u32_e32 v64, vcc, s12, v130
	s_nop 1
	v_addc_co_u32_e32 v65, vcc, 0, v131, vcc
	global_store_short v[64:65], v68, off offset:512
	v_mov_b32_e32 v64, v221
	s_nop 0
	v_lshlrev_b32_e32 v64, 2, v64
	v_xor_b32_e32 v64, 0x80, v64
	ds_bpermute_b32 v68, v64, v51
	v_mov_b32_e32 v64, v221
	s_nop 0
	v_lshlrev_b32_e32 v64, 2, v64
	v_xor_b32_e32 v64, 0x80, v64
	ds_bpermute_b32 v69, v64, v35
	v_mov_b32_e32 v64, v221
	s_nop 0
	v_lshlrev_b32_e32 v64, 2, v64
	v_xor_b32_e32 v64, 0x80, v64
	ds_bpermute_b32 v70, v64, v52
	v_mov_b32_e32 v64, v221
	s_nop 0
	v_lshlrev_b32_e32 v64, 2, v64
	v_xor_b32_e32 v64, 0x80, v64
	ds_bpermute_b32 v71, v64, v36
	s_waitcnt lgkmcnt(3)
	v_cndmask_b32_e64 v64, v68, v66, s[0:1]
	v_mul_f32_e32 v64, v136, v64
	v_fmac_f32_e32 v64, v48, v137
	v_fmac_f32_e32 v64, v49, v139
	v_mul_f32_e32 v65, 0xbfb8aa3b, v64
	v_exp_f32_e32 v65, v65
	s_waitcnt lgkmcnt(2)
	v_cndmask_b32_e64 v66, v69, v67, s[0:1]
	s_waitcnt lgkmcnt(1)
	v_cndmask_b32_e64 v67, v70, v72, s[0:1]
	s_waitcnt lgkmcnt(0)
	v_cndmask_b32_e64 v72, v71, v73, s[0:1]
	v_add_f32_e32 v65, 1.0, v65
	v_rcp_f32_e32 v74, v65
	v_mul_f32_e32 v66, v138, v66
	v_fmac_f32_e32 v66, v32, v140
	v_fmac_f32_e32 v66, v33, v141
	v_mul_f32_e32 v73, v64, v74
	v_mov_b32_e32 v64, v73
	v_mul_f32_e32 v73, v49, v137
	v_fmac_f32_e32 v73, v48, v136
	v_fmac_f32_e32 v73, v50, v139
	v_mul_f32_e32 v48, 0xbfb8aa3b, v73
	v_exp_f32_e32 v48, v48
	v_mul_f32_e32 v64, v66, v64
	s_mov_b32 s12, 0x58000
	v_cvt_pk_bf16_f32 v66, v64, s0
	v_add_co_u32_e32 v64, vcc, s12, v130
	v_add_f32_e32 v48, 1.0, v48
	s_nop 0
	v_addc_co_u32_e32 v65, vcc, 0, v131, vcc
	global_store_short v[64:65], v66, off
	v_rcp_f32_e32 v65, v48
	v_mul_f32_e32 v66, v33, v140
	v_fmac_f32_e32 v66, v32, v138
	v_fmac_f32_e32 v66, v34, v141
	v_mul_f32_e32 v64, v50, v137
	v_fmac_f32_e32 v64, v49, v136
	v_mul_f32_e32 v32, v73, v65
	v_fmac_f32_e32 v64, v51, v139
	v_mul_f32_e32 v48, 0xbfb8aa3b, v64
	v_exp_f32_e32 v65, v48
	s_mov_b32 s12, 0x59000
	v_mul_f32_e32 v32, v66, v32
	v_add_co_u32_e32 v48, vcc, s12, v130
	v_cvt_pk_bf16_f32 v32, v32, s0
	s_nop 0
	v_addc_co_u32_e32 v49, vcc, 0, v131, vcc
	global_store_short v[48:49], v32, off offset:1536
	v_add_f32_e32 v32, 1.0, v65
	v_rcp_f32_e32 v49, v32
	v_mul_f32_e32 v65, v34, v140
	v_fmac_f32_e32 v65, v33, v138
	v_fmac_f32_e32 v65, v35, v141
	v_mul_f32_e32 v33, v64, v49
	v_mul_f32_e32 v49, v51, v137
	v_mov_b32_e32 v32, v33
	v_fmac_f32_e32 v49, v50, v136
	v_mul_f32_e32 v32, v65, v32
	v_fmac_f32_e32 v49, v139, v67
	v_cvt_pk_bf16_f32 v48, v32, s0
	v_mul_f32_e32 v32, 0xbfb8aa3b, v49
	v_exp_f32_e32 v50, v32
	s_mov_b32 s12, 0x5a000
	v_add_co_u32_e32 v32, vcc, s12, v130
	v_mul_f32_e32 v35, v35, v140
	s_nop 0
	v_addc_co_u32_e32 v33, vcc, 0, v131, vcc
	global_store_short v[32:33], v48, off offset:3072
	v_add_f32_e32 v32, 1.0, v50
	v_rcp_f32_e32 v48, v32
	v_fmac_f32_e32 v35, v34, v138
	v_fmac_f32_e32 v35, v141, v72
	s_mov_b32 s12, 0x5c000
	v_mul_f32_e32 v33, v49, v48
	v_mov_b32_e32 v32, v33
	v_mul_f32_e32 v32, v35, v32
	v_cvt_pk_bf16_f32 v34, v32, s0
	v_add_co_u32_e32 v32, vcc, s12, v130
	s_nop 1
	v_addc_co_u32_e32 v33, vcc, 0, v131, vcc
	global_store_short v[32:33], v34, off offset:512
	v_mov_b32_e32 v32, v221
	s_nop 0
	v_lshlrev_b32_e32 v32, 2, v32
	v_xor_b32_e32 v32, 0x80, v32
	ds_bpermute_b32 v34, v32, v55
	v_mov_b32_e32 v32, v221
	s_nop 0
	v_lshlrev_b32_e32 v32, 2, v32
	v_xor_b32_e32 v32, 0x80, v32
	ds_bpermute_b32 v35, v32, v39
	v_mov_b32_e32 v32, v221
	s_waitcnt lgkmcnt(0)
	v_cndmask_b32_e64 v50, v35, v69, s[0:1]
	v_lshlrev_b32_e32 v32, 2, v32
	v_xor_b32_e32 v32, 0x80, v32
	ds_bpermute_b32 v48, v32, v56
	v_mov_b32_e32 v32, v221
	v_mul_f32_e32 v50, v138, v50
	v_lshlrev_b32_e32 v32, 2, v32
	v_xor_b32_e32 v32, 0x80, v32
	ds_bpermute_b32 v49, v32, v40
	v_cndmask_b32_e64 v32, v34, v68, s[0:1]
	v_mul_f32_e32 v32, v136, v32
	v_fmac_f32_e32 v32, v52, v137
	v_fmac_f32_e32 v32, v53, v139
	v_mul_f32_e32 v33, 0xbfb8aa3b, v32
	v_exp_f32_e32 v33, v33
	v_fmac_f32_e32 v50, v36, v140
	v_fmac_f32_e32 v50, v37, v141
	s_waitcnt lgkmcnt(1)
	v_cndmask_b32_e64 v51, v48, v70, s[0:1]
	v_add_f32_e32 v33, 1.0, v33
	v_rcp_f32_e32 v66, v33
	s_mov_b32 s12, 0x63000
	s_waitcnt lgkmcnt(0)
	v_cndmask_b32_e64 v64, v49, v71, s[0:1]
	v_mul_f32_e32 v65, v32, v66
	v_mov_b32_e32 v32, v65
	v_mul_f32_e32 v65, v53, v137
	v_fmac_f32_e32 v65, v52, v136
	v_mul_f32_e32 v32, v50, v32
	v_fmac_f32_e32 v65, v54, v139
	v_cvt_pk_bf16_f32 v50, v32, s0
	v_mul_f32_e32 v32, 0xbfb8aa3b, v65
	v_exp_f32_e32 v52, v32
	v_add_co_u32_e32 v32, vcc, s12, v130
	s_nop 1
	v_addc_co_u32_e32 v33, vcc, 0, v131, vcc
	global_store_short v[32:33], v50, off
	v_add_f32_e32 v32, 1.0, v52
	v_rcp_f32_e32 v50, v32
	v_mul_f32_e32 v52, v37, v140
	v_fmac_f32_e32 v52, v36, v138
	v_fmac_f32_e32 v52, v38, v141
	v_mul_f32_e32 v33, v65, v50
	v_mul_f32_e32 v50, v54, v137
	v_mov_b32_e32 v32, v33
	v_fmac_f32_e32 v50, v53, v136
	v_mul_f32_e32 v32, v52, v32
	v_fmac_f32_e32 v50, v55, v139
	v_cvt_pk_bf16_f32 v36, v32, s0
	v_mul_f32_e32 v32, 0xbfb8aa3b, v50
	v_exp_f32_e32 v52, v32
	s_mov_b32 s12, 0x64000
	v_add_co_u32_e32 v32, vcc, s12, v130
	s_nop 1
	v_addc_co_u32_e32 v33, vcc, 0, v131, vcc
	global_store_short v[32:33], v36, off offset:1536
	v_add_f32_e32 v32, 1.0, v52
	v_rcp_f32_e32 v36, v32
	v_mul_f32_e32 v52, v38, v140
	v_fmac_f32_e32 v52, v37, v138
	v_fmac_f32_e32 v52, v39, v141
	v_mul_f32_e32 v33, v50, v36
	v_mul_f32_e32 v37, v55, v137
	v_mov_b32_e32 v32, v33
	v_fmac_f32_e32 v37, v54, v136
	v_mul_f32_e32 v32, v52, v32
	v_fmac_f32_e32 v37, v139, v51
	v_cvt_pk_bf16_f32 v36, v32, s0
	v_mul_f32_e32 v32, 0xbfb8aa3b, v37
	v_exp_f32_e32 v50, v32
	s_mov_b32 s12, 0x65000
	v_add_co_u32_e32 v32, vcc, s12, v130
	v_mul_f32_e32 v39, v39, v140
	s_nop 0
	v_addc_co_u32_e32 v33, vcc, 0, v131, vcc
	global_store_short v[32:33], v36, off offset:3072
	v_add_f32_e32 v32, 1.0, v50
	v_rcp_f32_e32 v36, v32
	v_fmac_f32_e32 v39, v38, v138
	v_fmac_f32_e32 v39, v141, v64
	s_mov_b32 s12, 0x67000
	v_mul_f32_e32 v33, v37, v36
	v_mov_b32_e32 v32, v33
	v_mul_f32_e32 v32, v39, v32
	v_cvt_pk_bf16_f32 v36, v32, s0
	v_add_co_u32_e32 v32, vcc, s12, v130
	s_nop 1
	v_addc_co_u32_e32 v33, vcc, 0, v131, vcc
	global_store_short v[32:33], v36, off offset:512
	v_mov_b32_e32 v32, v221
	s_nop 0
	v_lshlrev_b32_e32 v32, 2, v32
	v_xor_b32_e32 v32, 0x80, v32
	ds_bpermute_b32 v36, v32, v59
	v_mov_b32_e32 v32, v221
	s_nop 0
	v_lshlrev_b32_e32 v32, 2, v32
	v_xor_b32_e32 v32, 0x80, v32
	ds_bpermute_b32 v37, v32, v43
	v_mov_b32_e32 v32, v221
	s_nop 0
	v_lshlrev_b32_e32 v32, 2, v32
	v_xor_b32_e32 v32, 0x80, v32
	ds_bpermute_b32 v38, v32, v60
	v_mov_b32_e32 v32, v221
	s_nop 0
	v_lshlrev_b32_e32 v32, 2, v32
	v_xor_b32_e32 v32, 0x80, v32
	ds_bpermute_b32 v39, v32, v44
	s_waitcnt lgkmcnt(3)
	v_cndmask_b32_e64 v32, v36, v34, s[0:1]
	v_mul_f32_e32 v32, v136, v32
	v_fmac_f32_e32 v32, v56, v137
	v_fmac_f32_e32 v32, v57, v139
	v_mul_f32_e32 v33, 0xbfb8aa3b, v32
	v_exp_f32_e32 v33, v33
	s_waitcnt lgkmcnt(2)
	v_cndmask_b32_e64 v34, v37, v35, s[0:1]
	s_waitcnt lgkmcnt(1)
	v_cndmask_b32_e64 v35, v38, v48, s[0:1]
	s_waitcnt lgkmcnt(0)
	v_cndmask_b32_e64 v48, v39, v49, s[0:1]
	v_add_f32_e32 v33, 1.0, v33
	v_rcp_f32_e32 v50, v33
	v_mul_f32_e32 v34, v138, v34
	v_fmac_f32_e32 v34, v40, v140
	v_fmac_f32_e32 v34, v41, v141
	v_mul_f32_e32 v49, v32, v50
	v_mov_b32_e32 v32, v49
	v_mul_f32_e32 v49, v57, v137
	v_fmac_f32_e32 v49, v56, v136
	v_mul_f32_e32 v32, v34, v32
	v_fmac_f32_e32 v49, v58, v139
	v_cvt_pk_bf16_f32 v34, v32, s0
	v_mul_f32_e32 v32, 0xbfb8aa3b, v49
	v_exp_f32_e32 v50, v32
	s_mov_b32 s12, 0x6e000
	v_add_co_u32_e32 v32, vcc, s12, v130
	s_nop 1
	v_addc_co_u32_e32 v33, vcc, 0, v131, vcc
	global_store_short v[32:33], v34, off
	v_add_f32_e32 v32, 1.0, v50
	v_rcp_f32_e32 v34, v32
	v_mul_f32_e32 v50, v41, v140
	v_fmac_f32_e32 v50, v40, v138
	v_fmac_f32_e32 v50, v42, v141
	v_mul_f32_e32 v33, v49, v34
	v_mul_f32_e32 v40, v58, v137
	v_mov_b32_e32 v32, v33
	v_fmac_f32_e32 v40, v57, v136
	v_mul_f32_e32 v32, v50, v32
	v_fmac_f32_e32 v40, v59, v139
	v_cvt_pk_bf16_f32 v34, v32, s0
	v_mul_f32_e32 v32, 0xbfb8aa3b, v40
	v_exp_f32_e32 v49, v32
	s_mov_b32 s12, 0x6f000
	v_add_co_u32_e32 v32, vcc, s12, v130
	s_nop 1
	v_addc_co_u32_e32 v33, vcc, 0, v131, vcc
	global_store_short v[32:33], v34, off offset:1536
	v_add_f32_e32 v32, 1.0, v49
	v_rcp_f32_e32 v34, v32
	v_mul_f32_e32 v49, v42, v140
	v_fmac_f32_e32 v49, v41, v138
	v_fmac_f32_e32 v49, v43, v141
	v_mul_f32_e32 v33, v40, v34
	v_mov_b32_e32 v32, v33
	v_mul_f32_e32 v40, v59, v137
	v_fmac_f32_e32 v40, v58, v136
	v_mul_f32_e32 v32, v49, v32
	v_fmac_f32_e32 v40, v139, v35
	v_cvt_pk_bf16_f32 v34, v32, s0
	v_mul_f32_e32 v32, 0xbfb8aa3b, v40
	v_exp_f32_e32 v35, v32
	s_mov_b32 s12, 0x70000
	v_add_co_u32_e32 v32, vcc, s12, v130
	s_nop 1
	v_addc_co_u32_e32 v33, vcc, 0, v131, vcc
	global_store_short v[32:33], v34, off offset:3072
	v_add_f32_e32 v32, 1.0, v35
	v_rcp_f32_e32 v34, v32
	v_mul_f32_e32 v35, v43, v140
	v_fmac_f32_e32 v35, v42, v138
	v_fmac_f32_e32 v35, v141, v48
	v_mul_f32_e32 v33, v40, v34
	v_mov_b32_e32 v32, v33
	v_mul_f32_e32 v32, v35, v32
	s_mov_b32 s12, 0x72000
	v_cvt_pk_bf16_f32 v34, v32, s0
	v_add_co_u32_e32 v32, vcc, s12, v130
	s_nop 1
	v_addc_co_u32_e32 v33, vcc, 0, v131, vcc
	global_store_short v[32:33], v34, off offset:512
	v_mov_b32_e32 v32, v221
	s_nop 0
	v_lshlrev_b32_e32 v32, 2, v32
	v_xor_b32_e32 v32, 0x80, v32
	ds_bpermute_b32 v34, v32, v63
	v_mov_b32_e32 v32, v221
	s_nop 0
	v_lshlrev_b32_e32 v32, 2, v32
	v_xor_b32_e32 v32, 0x80, v32
	ds_bpermute_b32 v35, v32, v47
	v_mov_b32_e32 v32, v221
	s_nop 0
	v_lshlrev_b32_e32 v32, 2, v32
	v_xor_b32_e32 v32, 0x80, v32
	ds_bpermute_b32 v40, v32, v16
	v_mov_b32_e32 v32, v221
	s_nop 0
	v_lshlrev_b32_e32 v32, 2, v32
	v_xor_b32_e32 v32, 0x80, v32
	ds_bpermute_b32 v41, v32, v0
	s_waitcnt lgkmcnt(3)
	v_cndmask_b32_e64 v32, v34, v36, s[0:1]
	v_mul_f32_e32 v32, v136, v32
	v_fmac_f32_e32 v32, v60, v137
	v_fmac_f32_e32 v32, v61, v139
	v_mul_f32_e32 v33, 0xbfb8aa3b, v32
	v_exp_f32_e32 v33, v33
	s_waitcnt lgkmcnt(2)
	v_cndmask_b32_e64 v36, v35, v37, s[0:1]
	s_waitcnt lgkmcnt(1)
	v_cndmask_b32_e64 v37, v40, v38, s[0:1]
	s_waitcnt lgkmcnt(0)
	v_cndmask_b32_e64 v38, v41, v39, s[0:1]
	v_add_f32_e32 v33, 1.0, v33
	v_rcp_f32_e32 v42, v33
	v_mul_f32_e32 v36, v138, v36
	v_fmac_f32_e32 v36, v44, v140
	v_fmac_f32_e32 v36, v45, v141
	v_mul_f32_e32 v39, v32, v42
	v_mov_b32_e32 v32, v39
	v_mul_f32_e32 v39, v61, v137
	v_fmac_f32_e32 v39, v60, v136
	v_mul_f32_e32 v32, v36, v32
	v_fmac_f32_e32 v39, v62, v139
	v_cvt_pk_bf16_f32 v36, v32, s0
	v_mul_f32_e32 v32, 0xbfb8aa3b, v39
	v_exp_f32_e32 v42, v32
	s_mov_b32 s12, 0x79000
	v_add_co_u32_e32 v32, vcc, s12, v130
	s_nop 1
	v_addc_co_u32_e32 v33, vcc, 0, v131, vcc
	global_store_short v[32:33], v36, off
	v_add_f32_e32 v32, 1.0, v42
	v_rcp_f32_e32 v36, v32
	v_mul_f32_e32 v42, v45, v140
	v_fmac_f32_e32 v42, v44, v138
	v_fmac_f32_e32 v42, v46, v141
	v_mul_f32_e32 v33, v39, v36
	v_mov_b32_e32 v32, v33
	v_mul_f32_e32 v39, v62, v137
	v_fmac_f32_e32 v39, v61, v136
	v_mul_f32_e32 v32, v42, v32
	v_fmac_f32_e32 v39, v63, v139
	v_cvt_pk_bf16_f32 v36, v32, s0
	v_mul_f32_e32 v32, 0xbfb8aa3b, v39
	v_exp_f32_e32 v42, v32
	s_mov_b32 s12, 0x7a000
	v_add_co_u32_e32 v32, vcc, s12, v130
	s_nop 1
	v_addc_co_u32_e32 v33, vcc, 0, v131, vcc
	global_store_short v[32:33], v36, off offset:1536
	v_add_f32_e32 v32, 1.0, v42
	v_rcp_f32_e32 v36, v32
	v_mul_f32_e32 v42, v46, v140
	v_fmac_f32_e32 v42, v45, v138
	v_fmac_f32_e32 v42, v47, v141
	v_mul_f32_e32 v33, v39, v36
	v_mov_b32_e32 v32, v33
	v_mul_f32_e32 v39, v63, v137
	v_fmac_f32_e32 v39, v62, v136
	v_mul_f32_e32 v32, v42, v32
	v_fmac_f32_e32 v39, v139, v37
	v_cvt_pk_bf16_f32 v36, v32, s0
	v_mul_f32_e32 v32, 0xbfb8aa3b, v39
	v_exp_f32_e32 v37, v32
	s_mov_b32 s12, 0x7b000
	v_add_co_u32_e32 v32, vcc, s12, v130
	s_nop 1
	v_addc_co_u32_e32 v33, vcc, 0, v131, vcc
	global_store_short v[32:33], v36, off offset:3072
	v_add_f32_e32 v32, 1.0, v37
	v_rcp_f32_e32 v36, v32
	v_mul_f32_e32 v37, v47, v140
	v_fmac_f32_e32 v37, v46, v138
	v_fmac_f32_e32 v37, v141, v38
	v_mul_f32_e32 v33, v39, v36
	v_mov_b32_e32 v32, v33
	v_mul_f32_e32 v32, v37, v32
	s_mov_b32 s12, 0x7d000
	v_cvt_pk_bf16_f32 v36, v32, s0
	v_add_co_u32_e32 v32, vcc, s12, v130
	s_nop 1
	v_addc_co_u32_e32 v33, vcc, 0, v131, vcc
	global_store_short v[32:33], v36, off offset:512
	v_mov_b32_e32 v32, v221
	s_nop 0
	v_lshlrev_b32_e32 v32, 2, v32
	v_xor_b32_e32 v32, 0x80, v32
	ds_bpermute_b32 v36, v32, v19
	v_mov_b32_e32 v32, v221
	s_nop 0
	v_lshlrev_b32_e32 v32, 2, v32
	v_xor_b32_e32 v32, 0x80, v32
	ds_bpermute_b32 v37, v32, v3
	v_mov_b32_e32 v32, v221
	s_nop 0
	v_lshlrev_b32_e32 v32, 2, v32
	v_xor_b32_e32 v32, 0x80, v32
	ds_bpermute_b32 v38, v32, v20
	v_mov_b32_e32 v32, v221
	s_nop 0
	v_lshlrev_b32_e32 v32, 2, v32
	v_xor_b32_e32 v32, 0x80, v32
	ds_bpermute_b32 v39, v32, v4
	s_waitcnt lgkmcnt(3)
	v_cndmask_b32_e64 v32, v36, v34, s[0:1]
	v_mul_f32_e32 v32, v136, v32
	v_fmac_f32_e32 v32, v16, v137
	v_fmac_f32_e32 v32, v17, v139
	v_mul_f32_e32 v33, 0xbfb8aa3b, v32
	v_exp_f32_e32 v33, v33
	s_waitcnt lgkmcnt(2)
	v_cndmask_b32_e64 v34, v37, v35, s[0:1]
	s_waitcnt lgkmcnt(1)
	v_cndmask_b32_e64 v35, v38, v40, s[0:1]
	s_waitcnt lgkmcnt(0)
	v_cndmask_b32_e64 v40, v39, v41, s[0:1]
	v_add_f32_e32 v33, 1.0, v33
	v_rcp_f32_e32 v42, v33
	v_mul_f32_e32 v34, v138, v34
	v_fmac_f32_e32 v34, v0, v140
	v_fmac_f32_e32 v34, v1, v141
	v_mul_f32_e32 v41, v32, v42
	v_mov_b32_e32 v32, v41
	v_mul_f32_e32 v41, v17, v137
	v_fmac_f32_e32 v41, v16, v136
	v_fmac_f32_e32 v41, v18, v139
	v_mul_f32_e32 v16, 0xbfb8aa3b, v41
	v_exp_f32_e32 v16, v16
	v_mul_f32_e32 v32, v34, v32
	s_mov_b32 s12, 0x84000
	v_cvt_pk_bf16_f32 v34, v32, s0
	v_add_co_u32_e32 v32, vcc, s12, v130
	v_add_f32_e32 v16, 1.0, v16
	s_nop 0
	v_addc_co_u32_e32 v33, vcc, 0, v131, vcc
	global_store_short v[32:33], v34, off
	v_rcp_f32_e32 v33, v16
	v_mul_f32_e32 v34, v1, v140
	v_fmac_f32_e32 v34, v0, v138
	v_fmac_f32_e32 v34, v2, v141
	v_mul_f32_e32 v32, v18, v137
	v_fmac_f32_e32 v32, v17, v136
	v_mul_f32_e32 v0, v41, v33
	v_fmac_f32_e32 v32, v19, v139
	v_mul_f32_e32 v16, 0xbfb8aa3b, v32
	v_exp_f32_e32 v33, v16
	s_mov_b32 s12, 0x85000
	v_mul_f32_e32 v0, v34, v0
	v_add_co_u32_e32 v16, vcc, s12, v130
	v_cvt_pk_bf16_f32 v0, v0, s0
	s_nop 0
	v_addc_co_u32_e32 v17, vcc, 0, v131, vcc
	global_store_short v[16:17], v0, off offset:1536
	v_add_f32_e32 v0, 1.0, v33
	v_rcp_f32_e32 v17, v0
	v_mul_f32_e32 v33, v2, v140
	v_fmac_f32_e32 v33, v1, v138
	v_fmac_f32_e32 v33, v3, v141
	v_mul_f32_e32 v1, v32, v17
	v_mul_f32_e32 v17, v19, v137
	v_mov_b32_e32 v0, v1
	v_fmac_f32_e32 v17, v18, v136
	v_mul_f32_e32 v0, v33, v0
	v_fmac_f32_e32 v17, v139, v35
	v_cvt_pk_bf16_f32 v16, v0, s0
	v_mul_f32_e32 v0, 0xbfb8aa3b, v17
	v_exp_f32_e32 v18, v0
	s_mov_b32 s12, 0x86000
	v_add_co_u32_e32 v0, vcc, s12, v130
	v_mul_f32_e32 v3, v3, v140
	s_nop 0
	v_addc_co_u32_e32 v1, vcc, 0, v131, vcc
	global_store_short v[0:1], v16, off offset:3072
	v_add_f32_e32 v0, 1.0, v18
	v_rcp_f32_e32 v16, v0
	v_fmac_f32_e32 v3, v2, v138
	v_fmac_f32_e32 v3, v141, v40
	s_mov_b32 s12, 0x88000
	v_mul_f32_e32 v1, v17, v16
	v_mov_b32_e32 v0, v1
	v_mul_f32_e32 v0, v3, v0
	v_cvt_pk_bf16_f32 v2, v0, s0
	v_add_co_u32_e32 v0, vcc, s12, v130
	s_nop 1
	v_addc_co_u32_e32 v1, vcc, 0, v131, vcc
	global_store_short v[0:1], v2, off offset:512
	v_mov_b32_e32 v0, v221
	s_nop 0
	v_lshlrev_b32_e32 v0, 2, v0
	v_xor_b32_e32 v0, 0x80, v0
	ds_bpermute_b32 v2, v0, v23
	v_mov_b32_e32 v0, v221
	s_nop 0
	v_lshlrev_b32_e32 v0, 2, v0
	v_xor_b32_e32 v0, 0x80, v0
	ds_bpermute_b32 v3, v0, v7
	v_mov_b32_e32 v0, v221
	s_waitcnt lgkmcnt(0)
	v_cndmask_b32_e64 v18, v3, v37, s[0:1]
	v_lshlrev_b32_e32 v0, 2, v0
	v_xor_b32_e32 v0, 0x80, v0
	ds_bpermute_b32 v16, v0, v24
	v_mov_b32_e32 v0, v221
	v_mul_f32_e32 v18, v138, v18
	v_lshlrev_b32_e32 v0, 2, v0
	v_xor_b32_e32 v0, 0x80, v0
	ds_bpermute_b32 v17, v0, v8
	v_cndmask_b32_e64 v0, v2, v36, s[0:1]
	v_mul_f32_e32 v0, v136, v0
	v_fmac_f32_e32 v0, v20, v137
	v_fmac_f32_e32 v0, v21, v139
	v_mul_f32_e32 v1, 0xbfb8aa3b, v0
	v_exp_f32_e32 v1, v1
	v_fmac_f32_e32 v18, v4, v140
	v_fmac_f32_e32 v18, v5, v141
	s_waitcnt lgkmcnt(1)
	v_cndmask_b32_e64 v19, v16, v38, s[0:1]
	v_add_f32_e32 v1, 1.0, v1
	v_rcp_f32_e32 v34, v1
	s_mov_b32 s12, 0x8f000
	s_waitcnt lgkmcnt(0)
	v_cndmask_b32_e64 v32, v17, v39, s[0:1]
	v_mul_f32_e32 v33, v0, v34
	v_mov_b32_e32 v0, v33
	v_mul_f32_e32 v33, v21, v137
	v_fmac_f32_e32 v33, v20, v136
	v_mul_f32_e32 v0, v18, v0
	v_fmac_f32_e32 v33, v22, v139
	v_cvt_pk_bf16_f32 v18, v0, s0
	v_mul_f32_e32 v0, 0xbfb8aa3b, v33
	v_exp_f32_e32 v20, v0
	v_add_co_u32_e32 v0, vcc, s12, v130
	s_nop 1
	v_addc_co_u32_e32 v1, vcc, 0, v131, vcc
	global_store_short v[0:1], v18, off
	v_add_f32_e32 v0, 1.0, v20
	v_rcp_f32_e32 v18, v0
	v_mul_f32_e32 v20, v5, v140
	v_fmac_f32_e32 v20, v4, v138
	v_fmac_f32_e32 v20, v6, v141
	v_mul_f32_e32 v1, v33, v18
	v_mul_f32_e32 v18, v22, v137
	v_mov_b32_e32 v0, v1
	v_fmac_f32_e32 v18, v21, v136
	v_mul_f32_e32 v0, v20, v0
	v_fmac_f32_e32 v18, v23, v139
	v_cvt_pk_bf16_f32 v4, v0, s0
	v_mul_f32_e32 v0, 0xbfb8aa3b, v18
	v_exp_f32_e32 v20, v0
	s_mov_b32 s12, 0x90000
	v_add_co_u32_e32 v0, vcc, s12, v130
	s_nop 1
	v_addc_co_u32_e32 v1, vcc, 0, v131, vcc
	global_store_short v[0:1], v4, off offset:1536
	v_add_f32_e32 v0, 1.0, v20
	v_rcp_f32_e32 v4, v0
	v_mul_f32_e32 v20, v6, v140
	v_fmac_f32_e32 v20, v5, v138
	v_fmac_f32_e32 v20, v7, v141
	v_mul_f32_e32 v1, v18, v4
	v_mul_f32_e32 v5, v23, v137
	v_mov_b32_e32 v0, v1
	v_fmac_f32_e32 v5, v22, v136
	v_mul_f32_e32 v0, v20, v0
	v_fmac_f32_e32 v5, v139, v19
	v_cvt_pk_bf16_f32 v4, v0, s0
	v_mul_f32_e32 v0, 0xbfb8aa3b, v5
	v_exp_f32_e32 v18, v0
	s_mov_b32 s12, 0x91000
	v_add_co_u32_e32 v0, vcc, s12, v130
	v_mul_f32_e32 v7, v7, v140
	s_nop 0
	v_addc_co_u32_e32 v1, vcc, 0, v131, vcc
	global_store_short v[0:1], v4, off offset:3072
	v_add_f32_e32 v0, 1.0, v18
	v_rcp_f32_e32 v4, v0
	v_fmac_f32_e32 v7, v6, v138
	v_fmac_f32_e32 v7, v141, v32
	s_mov_b32 s12, 0x93000
	v_mul_f32_e32 v1, v5, v4
	v_mov_b32_e32 v0, v1
	v_mul_f32_e32 v0, v7, v0
	v_cvt_pk_bf16_f32 v4, v0, s0
	v_add_co_u32_e32 v0, vcc, s12, v130
	s_nop 1
	v_addc_co_u32_e32 v1, vcc, 0, v131, vcc
	global_store_short v[0:1], v4, off offset:512
	v_mov_b32_e32 v0, v221
	s_nop 0
	v_lshlrev_b32_e32 v0, 2, v0
	v_xor_b32_e32 v0, 0x80, v0
	ds_bpermute_b32 v4, v0, v27
	v_mov_b32_e32 v0, v221
	s_nop 0
	v_lshlrev_b32_e32 v0, 2, v0
	v_xor_b32_e32 v0, 0x80, v0
	ds_bpermute_b32 v5, v0, v11
	v_mov_b32_e32 v0, v221
	s_nop 0
	v_lshlrev_b32_e32 v0, 2, v0
	v_xor_b32_e32 v0, 0x80, v0
	ds_bpermute_b32 v6, v0, v28
	v_mov_b32_e32 v0, v221
	s_nop 0
	v_lshlrev_b32_e32 v0, 2, v0
	v_xor_b32_e32 v0, 0x80, v0
	ds_bpermute_b32 v7, v0, v12
	s_waitcnt lgkmcnt(3)
	v_cndmask_b32_e64 v0, v4, v2, s[0:1]
	v_mul_f32_e32 v0, v136, v0
	v_fmac_f32_e32 v0, v24, v137
	v_fmac_f32_e32 v0, v25, v139
	v_mul_f32_e32 v1, 0xbfb8aa3b, v0
	v_exp_f32_e32 v1, v1
	s_waitcnt lgkmcnt(2)
	v_cndmask_b32_e64 v2, v5, v3, s[0:1]
	s_waitcnt lgkmcnt(1)
	v_cndmask_b32_e64 v3, v6, v16, s[0:1]
	s_waitcnt lgkmcnt(0)
	v_cndmask_b32_e64 v16, v7, v17, s[0:1]
	v_add_f32_e32 v1, 1.0, v1
	v_rcp_f32_e32 v18, v1
	v_mul_f32_e32 v2, v138, v2
	v_fmac_f32_e32 v2, v8, v140
	v_fmac_f32_e32 v2, v9, v141
	v_mul_f32_e32 v17, v0, v18
	v_mov_b32_e32 v0, v17
	v_mul_f32_e32 v17, v25, v137
	v_fmac_f32_e32 v17, v24, v136
	v_mul_f32_e32 v0, v2, v0
	v_fmac_f32_e32 v17, v26, v139
	v_cvt_pk_bf16_f32 v2, v0, s0
	v_mul_f32_e32 v0, 0xbfb8aa3b, v17
	v_exp_f32_e32 v18, v0
	s_mov_b32 s12, 0x9a000
	v_add_co_u32_e32 v0, vcc, s12, v130
	s_nop 1
	v_addc_co_u32_e32 v1, vcc, 0, v131, vcc
	global_store_short v[0:1], v2, off
	v_add_f32_e32 v0, 1.0, v18
	v_rcp_f32_e32 v2, v0
	v_mul_f32_e32 v18, v9, v140
	v_fmac_f32_e32 v18, v8, v138
	v_fmac_f32_e32 v18, v10, v141
	v_mul_f32_e32 v1, v17, v2
	v_mul_f32_e32 v8, v26, v137
	v_mov_b32_e32 v0, v1
	v_fmac_f32_e32 v8, v25, v136
	v_mul_f32_e32 v0, v18, v0
	v_fmac_f32_e32 v8, v27, v139
	v_cvt_pk_bf16_f32 v2, v0, s0
	v_mul_f32_e32 v0, 0xbfb8aa3b, v8
	v_exp_f32_e32 v17, v0
	s_mov_b32 s12, 0x9b000
	v_add_co_u32_e32 v0, vcc, s12, v130
	s_nop 1
	v_addc_co_u32_e32 v1, vcc, 0, v131, vcc
	global_store_short v[0:1], v2, off offset:1536
	v_add_f32_e32 v0, 1.0, v17
	v_rcp_f32_e32 v2, v0
	v_mul_f32_e32 v17, v10, v140
	v_fmac_f32_e32 v17, v9, v138
	v_fmac_f32_e32 v17, v11, v141
	v_mul_f32_e32 v1, v8, v2
	v_mov_b32_e32 v0, v1
	v_mul_f32_e32 v8, v27, v137
	v_fmac_f32_e32 v8, v26, v136
	v_mul_f32_e32 v0, v17, v0
	v_fmac_f32_e32 v8, v139, v3
	v_cvt_pk_bf16_f32 v2, v0, s0
	v_mul_f32_e32 v0, 0xbfb8aa3b, v8
	v_exp_f32_e32 v3, v0
	s_mov_b32 s12, 0x9c000
	v_add_co_u32_e32 v0, vcc, s12, v130
	s_nop 1
	v_addc_co_u32_e32 v1, vcc, 0, v131, vcc
	global_store_short v[0:1], v2, off offset:3072
	v_add_f32_e32 v0, 1.0, v3
	v_rcp_f32_e32 v2, v0
	v_mul_f32_e32 v3, v11, v140
	v_fmac_f32_e32 v3, v10, v138
	v_fmac_f32_e32 v3, v141, v16
	v_mul_f32_e32 v1, v8, v2
	v_mov_b32_e32 v0, v1
	v_mul_f32_e32 v0, v3, v0
	s_mov_b32 s12, 0x9e000
	v_cvt_pk_bf16_f32 v2, v0, s0
	v_add_co_u32_e32 v0, vcc, s12, v130
	s_nop 1
	v_addc_co_u32_e32 v1, vcc, 0, v131, vcc
	global_store_short v[0:1], v2, off offset:512
	v_mov_b32_e32 v0, v221
	v_mov_b32_e32 v1, v221
	v_lshlrev_b32_e32 v0, 2, v0
	v_xor_b32_e32 v0, 0x80, v0
	ds_bpermute_b32 v0, v0, v31
	s_waitcnt lgkmcnt(0)
	v_cndmask_b32_e64 v0, v0, v4, s[0:1]
	v_mul_f32_e32 v0, v136, v0
	v_fmac_f32_e32 v0, v28, v137
	v_fmac_f32_e32 v0, v29, v139
	v_mul_f32_e32 v2, 0xbfb8aa3b, v0
	v_exp_f32_e32 v2, v2
	v_lshlrev_b32_e32 v1, 2, v1
	v_xor_b32_e32 v1, 0x80, v1
	ds_bpermute_b32 v1, v1, v15
	v_add_f32_e32 v2, 1.0, v2
	v_rcp_f32_e32 v4, v2
	s_waitcnt lgkmcnt(0)
	v_cndmask_b32_e64 v1, v1, v5, s[0:1]
	v_mul_f32_e32 v1, v138, v1
	v_fmac_f32_e32 v1, v12, v140
	v_mul_f32_e32 v3, v0, v4
	v_mov_b32_e32 v0, v3
	v_mul_f32_e32 v3, v29, v137
	v_fmac_f32_e32 v1, v13, v141
	v_fmac_f32_e32 v3, v28, v136
	v_mul_f32_e32 v0, v1, v0
	v_fmac_f32_e32 v3, v139, v30
	v_cvt_pk_bf16_f32 v2, v0, s0
	v_mul_f32_e32 v0, 0xbfb8aa3b, v3
	v_exp_f32_e32 v4, v0
	s_mov_b32 s12, 0xa5000
	v_add_co_u32_e32 v0, vcc, s12, v130
	s_nop 1
	v_addc_co_u32_e32 v1, vcc, 0, v131, vcc
	global_store_short v[0:1], v2, off
	v_add_f32_e32 v0, 1.0, v4
	v_rcp_f32_e32 v2, v0
	v_mul_f32_e32 v4, v13, v140
	v_fmac_f32_e32 v4, v12, v138
	v_fmac_f32_e32 v4, v141, v14
	v_mul_f32_e32 v1, v3, v2
	v_mov_b32_e32 v0, v1
	v_mul_f32_e32 v3, v137, v30
	v_fmac_f32_e32 v3, v29, v136
	v_mul_f32_e32 v0, v4, v0
	v_fmac_f32_e32 v3, v139, v31
	v_cvt_pk_bf16_f32 v2, v0, s0
	v_mul_f32_e32 v0, 0xbfb8aa3b, v3
	v_exp_f32_e32 v4, v0
	s_mov_b32 s12, 0xa6000
	v_add_co_u32_e32 v0, vcc, s12, v130
	s_nop 1
	v_addc_co_u32_e32 v1, vcc, 0, v131, vcc
	global_store_short v[0:1], v2, off offset:1536
	v_add_f32_e32 v0, 1.0, v4
	v_rcp_f32_e32 v2, v0
	v_mul_f32_e32 v4, v140, v14
	v_fmac_f32_e32 v4, v13, v138
	v_fmac_f32_e32 v4, v141, v15
	v_mul_f32_e32 v1, v3, v2
	v_mov_b32_e32 v0, v1
	v_mul_f32_e32 v0, v4, v0
	v_mul_f32_e32 v3, v136, v30
	v_cvt_pk_bf16_f32 v2, v0, s0
	v_cndmask_b32_e64 v0, 0, v6, s[0:1]
	v_fmac_f32_e32 v3, v137, v31
	v_fmac_f32_e32 v3, v139, v0
	v_mul_f32_e32 v0, 0xbfb8aa3b, v3
	v_exp_f32_e32 v4, v0
	s_mov_b32 s12, 0xa7000
	v_add_co_u32_e32 v0, vcc, s12, v130
	v_mul_f32_e32 v5, v138, v14
	s_nop 0
	v_addc_co_u32_e32 v1, vcc, 0, v131, vcc
	global_store_short v[0:1], v2, off offset:3072
	v_add_f32_e32 v1, 1.0, v4
	v_rcp_f32_e32 v4, v1
	v_cndmask_b32_e64 v0, 0, v7, s[0:1]
	v_fmac_f32_e32 v5, v140, v15
	v_fmac_f32_e32 v5, v141, v0
	v_mul_f32_e32 v0, v3, v4
	v_readlane_b32 s12, v252, 7
	v_mul_f32_e32 v0, v5, v0
	s_add_i32 s14, s14, s12
	s_add_i32 s15, s15, s12
	v_readlane_b32 s12, v252, 8
	v_cvt_pk_bf16_f32 v2, v0, s0
	v_add_co_u32_e32 v0, vcc, 0xa9000, v130
	s_add_i32 s17, s17, s12
	s_nop 0
	v_addc_co_u32_e32 v1, vcc, 0, v131, vcc
	s_cmpk_lt_i32 s14, 0xb0
	global_store_short v[0:1], v2, off offset:512
	s_cbranch_scc0 .LBB0_2345
.LBB0_2339:
	s_and_b32 s12, s15, 7
	v_lshl_add_u32 v0, s12, 8, v186
	v_ashrrev_i32_e32 v1, 31, v0
	v_lshlrev_b64 v[0:1], 11, v[0:1]
	s_and_b32 s12, s17, 0xffffff00
	v_lshl_add_u64 v[170:171], v[160:161], 0, v[0:1]
	v_add_u32_e32 v0, s12, v175
	s_and_b32 s12, s14, 7
	v_ashrrev_i32_e32 v1, 31, v0
	s_or_b32 s12, s12, s16
	v_lshlrev_b64 v[0:1], 11, v[0:1]
	s_lshl_b32 s13, s12, 8
	v_lshl_add_u64 v[172:173], v[168:169], 0, v[0:1]
	v_add_u32_e32 v0, s13, v175
	s_lshl_b32 s12, s14, 5
	v_ashrrev_i32_e32 v1, 31, v0
	s_and_b32 s12, s12, 0xffffff00
	v_lshlrev_b64 v[0:1], 11, v[0:1]
	v_add_u32_e32 v2, s12, v175
	s_cmp_eq_u32 s101, 0
	s_cbranch_scc1 .Lpf_cold_up
	s_mov_b32 s101, 0
	s_branch .Lpf_after_up
.Lpf_cold_up:
	s_waitcnt vmcnt(0) lgkmcnt(0)
	s_barrier
	v_ashrrev_i32_e32 v3, 31, v2
	v_lshl_add_u64 v[0:1], v[156:157], 0, v[0:1]
	v_readfirstlane_b32 s18, v180
	s_mov_b32 m0, s18
	s_nop 0
	global_load_lds_dwordx4 v[0:1], off
	v_lshlrev_b64 v[2:3], 11, v[2:3]
	v_lshl_add_u64 v[4:5], v[0:1], 0, s[34:35]
	s_add_i32 s19, s18, 0x2000
	s_mov_b32 m0, s19
	s_nop 0
	global_load_lds_dwordx4 v[4:5], off
	v_lshl_add_u64 v[2:3], v[158:159], 0, v[2:3]
	s_add_i32 s19, s18, 0x4000
	s_mov_b32 m0, s19
	s_nop 0
	global_load_lds_dwordx4 v[2:3], off
	v_lshl_add_u64 v[4:5], v[2:3], 0, s[34:35]
	s_add_i32 s19, s18, 0x6000
	s_mov_b32 m0, s19
	s_nop 0
	global_load_lds_dwordx4 v[4:5], off
	s_add_i32 s19, s18, 0x8000
	v_lshl_add_u64 v[4:5], v[0:1], 0, 64
	s_mov_b32 m0, s19
	s_nop 0
	global_load_lds_dwordx4 v[4:5], off
	s_mov_b64 s[20:21], 0x40040
	v_lshl_add_u64 v[4:5], v[0:1], 0, s[20:21]
	s_add_i32 s19, s18, 0xa000
	s_mov_b32 m0, s19
	s_nop 0
	global_load_lds_dwordx4 v[4:5], off
	v_lshl_add_u64 v[4:5], v[2:3], 0, 64
	s_add_i32 s19, s18, 0xc000
	s_mov_b32 m0, s19
	s_nop 0
	global_load_lds_dwordx4 v[4:5], off
	v_lshl_add_u64 v[4:5], v[2:3], 0, s[20:21]
	s_add_i32 s19, s18, 0xe000
	s_mov_b32 m0, s19
	s_nop 0
	global_load_lds_dwordx4 v[4:5], off
	s_mov_b64 s[20:21], 0x80
	s_add_i32 s19, s18, 0x10000
	v_lshl_add_u64 v[4:5], v[0:1], 0, s[20:21]
	s_mov_b32 m0, s19
	s_nop 0
	global_load_lds_dwordx4 v[4:5], off
	s_mov_b64 s[22:23], 0x40080
	v_lshl_add_u64 v[0:1], v[0:1], 0, s[22:23]
	s_add_i32 s19, s18, 0x12000
	s_mov_b32 m0, s19
	s_nop 0
	global_load_lds_dwordx4 v[0:1], off
	v_lshl_add_u64 v[0:1], v[2:3], 0, s[20:21]
	s_add_i32 s19, s18, 0x14000
	s_mov_b32 m0, s19
	s_nop 0
	global_load_lds_dwordx4 v[0:1], off
	v_lshl_add_u64 v[0:1], v[2:3], 0, s[22:23]
	s_add_i32 s18, s18, 0x16000
	s_mov_b32 m0, s18
	s_nop 0
	global_load_lds_dwordx4 v[0:1], off
.Lpf_after_up:
	v_mov_b32_e32 v130, 0
	v_mov_b32_e32 v134, 0
	v_mov_b32_e32 v0, 0
	s_mov_b32 s18, 0x18000
	v_mov_b32_e32 v1, v0
	v_mov_b32_e32 v2, v0
	v_mov_b32_e32 v3, v0
	v_mov_b32_e32 v4, v0
	v_mov_b32_e32 v5, v0
	v_mov_b32_e32 v6, v0
	v_mov_b32_e32 v7, v0
	v_mov_b32_e32 v8, v0
	v_mov_b32_e32 v9, v0
	v_mov_b32_e32 v10, v0
	v_mov_b32_e32 v11, v0
	v_mov_b32_e32 v12, v0
	v_mov_b32_e32 v13, v0
	v_mov_b32_e32 v14, v0
	v_mov_b32_e32 v15, v0
	v_mov_b32_e32 v16, v0
	v_mov_b32_e32 v17, v0
	v_mov_b32_e32 v18, v0
	v_mov_b32_e32 v19, v0
	v_mov_b32_e32 v20, v0
	v_mov_b32_e32 v21, v0
	v_mov_b32_e32 v22, v0
	v_mov_b32_e32 v23, v0
	v_mov_b32_e32 v24, v0
	v_mov_b32_e32 v25, v0
	v_mov_b32_e32 v26, v0
	v_mov_b32_e32 v27, v0
	v_mov_b32_e32 v28, v0
	v_mov_b32_e32 v29, v0
	v_mov_b32_e32 v30, v0
	v_mov_b32_e32 v31, v0
	v_mov_b32_e32 v32, v0
	v_mov_b32_e32 v33, v0
	v_mov_b32_e32 v34, v0
	v_mov_b32_e32 v35, v0
	v_mov_b32_e32 v36, v0
	v_mov_b32_e32 v37, v0
	v_mov_b32_e32 v38, v0
	v_mov_b32_e32 v39, v0
	v_mov_b32_e32 v40, v0
	v_mov_b32_e32 v41, v0
	v_mov_b32_e32 v42, v0
	v_mov_b32_e32 v43, v0
	v_mov_b32_e32 v44, v0
	v_mov_b32_e32 v45, v0
	v_mov_b32_e32 v46, v0
	v_mov_b32_e32 v47, v0
	v_mov_b32_e32 v48, v0
	v_mov_b32_e32 v49, v0
	v_mov_b32_e32 v50, v0
	v_mov_b32_e32 v51, v0
	v_mov_b32_e32 v52, v0
	v_mov_b32_e32 v53, v0
	v_mov_b32_e32 v54, v0
	v_mov_b32_e32 v55, v0
	v_mov_b32_e32 v56, v0
	v_mov_b32_e32 v57, v0
	v_mov_b32_e32 v58, v0
	v_mov_b32_e32 v59, v0
	v_mov_b32_e32 v60, v0
	v_mov_b32_e32 v61, v0
	v_mov_b32_e32 v62, v0
	v_mov_b32_e32 v63, v0
	v_mov_b32_e32 v64, v0
	v_mov_b32_e32 v65, v0
	v_mov_b32_e32 v66, v0
	v_mov_b32_e32 v67, v0
	v_mov_b32_e32 v68, v0
	v_mov_b32_e32 v69, v0
	v_mov_b32_e32 v70, v0
	v_mov_b32_e32 v71, v0
	v_mov_b32_e32 v72, v0
	v_mov_b32_e32 v73, v0
	v_mov_b32_e32 v74, v0
	v_mov_b32_e32 v75, v0
	v_mov_b32_e32 v76, v0
	v_mov_b32_e32 v77, v0
	v_mov_b32_e32 v78, v0
	v_mov_b32_e32 v79, v0
	v_mov_b32_e32 v80, v0
	v_mov_b32_e32 v81, v0
	v_mov_b32_e32 v82, v0
	v_mov_b32_e32 v83, v0
	v_mov_b32_e32 v84, v0
	v_mov_b32_e32 v85, v0
	v_mov_b32_e32 v86, v0
	v_mov_b32_e32 v87, v0
	v_mov_b32_e32 v88, v0
	v_mov_b32_e32 v89, v0
	v_mov_b32_e32 v90, v0
	v_mov_b32_e32 v91, v0
	v_mov_b32_e32 v92, v0
	v_mov_b32_e32 v93, v0
	v_mov_b32_e32 v94, v0
	v_mov_b32_e32 v95, v0
	v_mov_b32_e32 v96, v0
	v_mov_b32_e32 v97, v0
	v_mov_b32_e32 v98, v0
	v_mov_b32_e32 v99, v0
	v_mov_b32_e32 v100, v0
	v_mov_b32_e32 v101, v0
	v_mov_b32_e32 v102, v0
	v_mov_b32_e32 v103, v0
	v_mov_b32_e32 v104, v0
	v_mov_b32_e32 v105, v0
	v_mov_b32_e32 v106, v0
	v_mov_b32_e32 v107, v0
	v_mov_b32_e32 v108, v0
	v_mov_b32_e32 v109, v0
	v_mov_b32_e32 v110, v0
	v_mov_b32_e32 v111, v0
	v_mov_b32_e32 v112, v0
	v_mov_b32_e32 v113, v0
	v_mov_b32_e32 v114, v0
	v_mov_b32_e32 v115, v0
	v_mov_b32_e32 v116, v0
	v_mov_b32_e32 v117, v0
	v_mov_b32_e32 v118, v0
	v_mov_b32_e32 v119, v0
	v_mov_b32_e32 v120, v0
	v_mov_b32_e32 v121, v0
	v_mov_b32_e32 v122, v0
	v_mov_b32_e32 v123, v0
	v_mov_b32_e32 v124, v0
	v_mov_b32_e32 v125, v0
	v_mov_b32_e32 v126, v0
	v_mov_b32_e32 v127, v0
	v_mov_b32_e32 v135, v134
	v_mov_b32_e32 v136, v134
	v_mov_b32_e32 v137, v134
	v_mov_b32_e32 v138, v134
	v_mov_b32_e32 v139, v134
	v_mov_b32_e32 v140, v134
	v_mov_b32_e32 v141, v134
	v_mov_b32_e32 v146, v134
	v_mov_b32_e32 v147, v134
	v_mov_b32_e32 v148, v134
	v_mov_b32_e32 v149, v134
	v_mov_b32_e32 v150, v134
	v_mov_b32_e32 v151, v134
	v_mov_b32_e32 v152, v134
	v_mov_b32_e32 v153, v134
	v_mov_b32_e32 v131, v130
	v_mov_b32_e32 v132, v130
	v_mov_b32_e32 v133, v130
	v_mov_b32_e32 v142, v130
	v_mov_b32_e32 v143, v130
	v_mov_b32_e32 v144, v130
	v_mov_b32_e32 v145, v130
.LBB0_2340:
	s_and_b32 s19, s18, 0x18000
	v_add_u32_e32 v187, s19, v180
	s_add_i32 s19, s18, 0xfffe8000
	s_and_b32 s19, s19, 0x18000
	v_or_b32_e32 v212, s19, v179
	v_add_u32_e32 v213, s19, v176
	s_waitcnt vmcnt(8) lgkmcnt(0)
	s_barrier
	v_mfma_f32_32x32x16_bf16 v[112:127], v[150:153], v[142:145], v[112:127]
	v_mfma_f32_32x32x16_bf16 v[96:111], v[150:153], v[130:133], v[96:111]
	v_add_u32_e32 v192, v212, v177
	v_add_u32_e32 v208, v213, v177
	ds_read_b128 v[188:191], v192 offset:16384
	ds_read_b128 v[192:195], v192 offset:18432
	ds_read_b128 v[196:199], v208
	ds_read_b128 v[200:203], v208 offset:2048
	ds_read_b128 v[204:207], v208 offset:4096
	ds_read_b128 v[208:211], v208 offset:6144
	v_mfma_f32_32x32x16_bf16 v[80:95], v[146:149], v[142:145], v[80:95]
	v_mfma_f32_32x32x16_bf16 v[64:79], v[146:149], v[130:133], v[64:79]
	v_readfirstlane_b32 s19, v187
	s_mov_b32 m0, s19
	s_nop 0
	global_load_lds_dwordx4 v[170:171], off
	v_mfma_f32_32x32x16_bf16 v[48:63], v[138:141], v[142:145], v[48:63]
	v_mfma_f32_32x32x16_bf16 v[32:47], v[138:141], v[130:133], v[32:47]
	s_add_i32 s20, s19, 0x2000
	v_lshl_add_u64 v[150:151], v[170:171], 0, s[34:35]
	s_mov_b32 m0, s20
	s_nop 0
	global_load_lds_dwordx4 v[150:151], off
	v_mfma_f32_32x32x16_bf16 v[16:31], v[134:137], v[142:145], v[16:31]
	v_mfma_f32_32x32x16_bf16 v[0:15], v[134:137], v[130:133], v[0:15]
	v_add_u32_e32 v130, v212, v178
	v_add_u32_e32 v134, v213, v178
	ds_read_b128 v[142:145], v130 offset:16384
	ds_read_b128 v[130:133], v130 offset:18432
	ds_read_b128 v[150:153], v134
	ds_read_b128 v[146:149], v134 offset:2048
	ds_read_b128 v[138:141], v134 offset:4096
	ds_read_b128 v[134:137], v134 offset:6144
	s_waitcnt lgkmcnt(9)
	v_mfma_f32_32x32x16_bf16 v[112:127], v[196:199], v[188:191], v[112:127]
	s_add_i32 s20, s19, 0x6000
	s_addk_i32 s19, 0x4000
	v_mfma_f32_32x32x16_bf16 v[96:111], v[196:199], v[192:195], v[96:111]
	s_mov_b32 m0, s19
	s_nop 0
	global_load_lds_dwordx4 v[172:173], off
	v_lshl_add_u64 v[212:213], v[172:173], 0, s[34:35]
	s_waitcnt lgkmcnt(8)
	v_mfma_f32_32x32x16_bf16 v[80:95], v[200:203], v[188:191], v[80:95]
	v_mfma_f32_32x32x16_bf16 v[64:79], v[200:203], v[192:195], v[64:79]
	s_waitcnt lgkmcnt(7)
	v_mfma_f32_32x32x16_bf16 v[48:63], v[204:207], v[188:191], v[48:63]
	v_mfma_f32_32x32x16_bf16 v[32:47], v[204:207], v[192:195], v[32:47]
	s_mov_b32 m0, s20
	s_nop 0
	global_load_lds_dwordx4 v[212:213], off
	s_waitcnt lgkmcnt(6)
	v_mfma_f32_32x32x16_bf16 v[16:31], v[208:211], v[188:191], v[16:31]
	s_add_i32 s18, s18, 0x8000
	v_lshl_add_u64 v[170:171], v[170:171], 0, 64
	v_lshl_add_u64 v[172:173], v[172:173], 0, 64
	s_cmp_eq_u32 s18, 0x100000
	v_mfma_f32_32x32x16_bf16 v[0:15], v[208:211], v[192:195], v[0:15]
	s_cbranch_scc0 .LBB0_2340
	s_waitcnt vmcnt(8) lgkmcnt(0)
	s_barrier
	v_add_u32_e32 v187, v179, v177
	ds_read_b128 v[170:173], v187 offset:49152
	ds_read_b128 v[188:191], v187 offset:51200
	v_add_u32_e32 v187, v176, v177
	ds_read_b128 v[192:195], v187 offset:32768
	ds_read_b128 v[196:199], v187 offset:34816
	ds_read_b128 v[200:203], v187 offset:36864
	ds_read_b128 v[204:207], v187 offset:38912
	s_waitcnt lgkmcnt(9)
	v_mfma_f32_32x32x16_bf16 v[112:127], v[150:153], v[142:145], v[112:127]
	v_mfma_f32_32x32x16_bf16 v[96:111], v[150:153], v[130:133], v[96:111]
	s_waitcnt lgkmcnt(8)
	v_mfma_f32_32x32x16_bf16 v[80:95], v[146:149], v[142:145], v[80:95]
	v_mfma_f32_32x32x16_bf16 v[64:79], v[146:149], v[130:133], v[64:79]
	s_waitcnt lgkmcnt(7)
	v_mfma_f32_32x32x16_bf16 v[48:63], v[138:141], v[142:145], v[48:63]
	v_mfma_f32_32x32x16_bf16 v[32:47], v[138:141], v[130:133], v[32:47]
	s_waitcnt lgkmcnt(6)
	v_mfma_f32_32x32x16_bf16 v[16:31], v[134:137], v[142:145], v[16:31]
	v_mfma_f32_32x32x16_bf16 v[0:15], v[134:137], v[130:133], v[0:15]
	v_add_u32_e32 v134, v179, v178
	v_add_u32_e32 v150, v176, v178
	ds_read_b128 v[130:133], v134 offset:49152
	ds_read_b128 v[134:137], v134 offset:51200
	ds_read_b128 v[138:141], v150 offset:32768
	ds_read_b128 v[142:145], v150 offset:34816
	ds_read_b128 v[146:149], v150 offset:36864
	ds_read_b128 v[150:153], v150 offset:38912
	s_waitcnt lgkmcnt(9)
	v_mfma_f32_32x32x16_bf16 v[112:127], v[192:195], v[170:173], v[112:127]
	v_mfma_f32_32x32x16_bf16 v[96:111], v[192:195], v[188:191], v[96:111]
	s_waitcnt lgkmcnt(8)
	v_mfma_f32_32x32x16_bf16 v[80:95], v[196:199], v[170:173], v[80:95]
	v_mfma_f32_32x32x16_bf16 v[64:79], v[196:199], v[188:191], v[64:79]
	s_waitcnt lgkmcnt(7)
	v_mfma_f32_32x32x16_bf16 v[48:63], v[200:203], v[170:173], v[48:63]
	v_mfma_f32_32x32x16_bf16 v[32:47], v[200:203], v[188:191], v[32:47]
	s_waitcnt vmcnt(4) lgkmcnt(0)
	s_barrier
	v_add_u32_e32 v187, v184, v177
	s_waitcnt lgkmcnt(6)
	v_mfma_f32_32x32x16_bf16 v[16:31], v[204:207], v[170:173], v[16:31]
	v_mfma_f32_32x32x16_bf16 v[0:15], v[204:207], v[188:191], v[0:15]
	ds_read_b128 v[170:173], v187 offset:16384
	ds_read_b128 v[188:191], v187 offset:18432
	v_add_u32_e32 v187, v185, v177
	ds_read_b128 v[192:195], v187
	ds_read_b128 v[196:199], v187 offset:2048
	ds_read_b128 v[200:203], v187 offset:4096
	ds_read_b128 v[204:207], v187 offset:6144
	s_waitcnt lgkmcnt(9)
	v_mfma_f32_32x32x16_bf16 v[112:127], v[138:141], v[130:133], v[112:127]
	v_mfma_f32_32x32x16_bf16 v[96:111], v[138:141], v[134:137], v[96:111]
	s_waitcnt lgkmcnt(8)
	v_mfma_f32_32x32x16_bf16 v[80:95], v[142:145], v[130:133], v[80:95]
	v_mfma_f32_32x32x16_bf16 v[64:79], v[142:145], v[134:137], v[64:79]
	s_waitcnt lgkmcnt(7)
	v_mfma_f32_32x32x16_bf16 v[48:63], v[146:149], v[130:133], v[48:63]
	v_mfma_f32_32x32x16_bf16 v[32:47], v[146:149], v[134:137], v[32:47]
	s_waitcnt lgkmcnt(6)
	v_mfma_f32_32x32x16_bf16 v[16:31], v[150:153], v[130:133], v[16:31]
	v_mfma_f32_32x32x16_bf16 v[0:15], v[150:153], v[134:137], v[0:15]
	v_add_u32_e32 v134, v184, v178
	v_add_u32_e32 v150, v185, v178
	ds_read_b128 v[130:133], v134 offset:16384
	ds_read_b128 v[134:137], v134 offset:18432
	ds_read_b128 v[138:141], v150
	ds_read_b128 v[142:145], v150 offset:2048
	ds_read_b128 v[146:149], v150 offset:4096
	ds_read_b128 v[150:153], v150 offset:6144
	s_waitcnt lgkmcnt(9)
	v_mfma_f32_32x32x16_bf16 v[112:127], v[192:195], v[170:173], v[112:127]
	v_mfma_f32_32x32x16_bf16 v[96:111], v[192:195], v[188:191], v[96:111]
	s_waitcnt lgkmcnt(8)
	v_mfma_f32_32x32x16_bf16 v[80:95], v[196:199], v[170:173], v[80:95]
	v_mfma_f32_32x32x16_bf16 v[64:79], v[196:199], v[188:191], v[64:79]
	s_waitcnt lgkmcnt(7)
	v_mfma_f32_32x32x16_bf16 v[48:63], v[200:203], v[170:173], v[48:63]
	v_mfma_f32_32x32x16_bf16 v[32:47], v[200:203], v[188:191], v[32:47]
	s_waitcnt vmcnt(0) lgkmcnt(0)
	s_barrier
	v_add_u32_e32 v187, v182, v177
	s_waitcnt lgkmcnt(6)
	v_mfma_f32_32x32x16_bf16 v[16:31], v[204:207], v[170:173], v[16:31]
	v_mfma_f32_32x32x16_bf16 v[0:15], v[204:207], v[188:191], v[0:15]
	ds_read_b128 v[170:173], v187 offset:16384
	ds_read_b128 v[188:191], v187 offset:18432
	v_add_u32_e32 v187, v183, v177
	ds_read_b128 v[192:195], v187
	ds_read_b128 v[196:199], v187 offset:2048
	ds_read_b128 v[200:203], v187 offset:4096
	ds_read_b128 v[204:207], v187 offset:6144
	s_waitcnt lgkmcnt(9)
	v_mfma_f32_32x32x16_bf16 v[112:127], v[138:141], v[130:133], v[112:127]
	v_mfma_f32_32x32x16_bf16 v[96:111], v[138:141], v[134:137], v[96:111]
	s_waitcnt lgkmcnt(8)
	v_mfma_f32_32x32x16_bf16 v[80:95], v[142:145], v[130:133], v[80:95]
	v_mfma_f32_32x32x16_bf16 v[64:79], v[142:145], v[134:137], v[64:79]
	s_waitcnt lgkmcnt(7)
	v_mfma_f32_32x32x16_bf16 v[48:63], v[146:149], v[130:133], v[48:63]
	v_mfma_f32_32x32x16_bf16 v[32:47], v[146:149], v[134:137], v[32:47]
	s_waitcnt lgkmcnt(6)
	v_mfma_f32_32x32x16_bf16 v[16:31], v[150:153], v[130:133], v[16:31]
	v_mfma_f32_32x32x16_bf16 v[0:15], v[150:153], v[134:137], v[0:15]
	v_add_u32_e32 v134, v182, v178
	v_add_u32_e32 v150, v183, v178
	ds_read_b128 v[130:133], v134 offset:16384
	ds_read_b128 v[134:137], v134 offset:18432
	ds_read_b128 v[138:141], v150
	ds_read_b128 v[142:145], v150 offset:2048
	ds_read_b128 v[146:149], v150 offset:4096
	ds_read_b128 v[150:153], v150 offset:6144
	s_waitcnt lgkmcnt(9)
	v_mfma_f32_32x32x16_bf16 v[112:127], v[192:195], v[170:173], v[112:127]
	v_mfma_f32_32x32x16_bf16 v[96:111], v[192:195], v[188:191], v[96:111]
	s_waitcnt lgkmcnt(8)
	v_mfma_f32_32x32x16_bf16 v[80:95], v[196:199], v[170:173], v[80:95]
	v_mfma_f32_32x32x16_bf16 v[64:79], v[196:199], v[188:191], v[64:79]
	s_waitcnt lgkmcnt(7)
	v_mfma_f32_32x32x16_bf16 v[48:63], v[200:203], v[170:173], v[48:63]
	v_mfma_f32_32x32x16_bf16 v[32:47], v[200:203], v[188:191], v[32:47]
	s_waitcnt lgkmcnt(6)
	v_mfma_f32_32x32x16_bf16 v[16:31], v[204:207], v[170:173], v[16:31]
	v_mfma_f32_32x32x16_bf16 v[0:15], v[204:207], v[188:191], v[0:15]
	s_waitcnt lgkmcnt(3)
	v_mfma_f32_32x32x16_bf16 v[112:127], v[138:141], v[130:133], v[112:127]
	s_waitcnt lgkmcnt(2)
	v_mfma_f32_32x32x16_bf16 v[80:95], v[142:145], v[130:133], v[80:95]
	s_waitcnt lgkmcnt(1)
	v_mfma_f32_32x32x16_bf16 v[48:63], v[146:149], v[130:133], v[48:63]
	s_waitcnt lgkmcnt(0)
	v_mfma_f32_32x32x16_bf16 v[16:31], v[150:153], v[130:133], v[16:31]
	v_or_b32_e32 v132, s12, v174
	v_ashrrev_i32_e32 v130, 1, v132
	v_or_b32_e32 v130, v130, v154
	v_ashrrev_i32_e32 v131, 31, v130
	s_movk_i32 s12, 0x5000
	v_mfma_f32_32x32x16_bf16 v[96:111], v[138:141], v[134:137], v[96:111]
	v_mfma_f32_32x32x16_bf16 v[64:79], v[142:145], v[134:137], v[64:79]
	v_add_u32_e32 v142, s13, v155
	s_mov_b32 s13, 0xb000
	v_ashrrev_i32_e32 v133, 7, v142
	v_mfma_f32_32x32x16_bf16 v[32:47], v[146:149], v[134:137], v[32:47]
	v_mfma_f32_32x32x16_bf16 v[0:15], v[150:153], v[134:137], v[0:15]
	v_lshl_add_u64 v[134:135], v[130:131], 2, s[10:11]
	v_add_co_u32_e32 v138, vcc, s12, v134
	s_mov_b32 s12, 0x8000
	s_nop 0
	v_addc_co_u32_e32 v139, vcc, 0, v135, vcc
	global_load_dword v137, v[138:139], off offset:2048
	v_add_co_u32_e32 v138, vcc, s13, v134
	global_load_dword v136, v[134:135], off
	s_nop 0
	v_addc_co_u32_e32 v139, vcc, 0, v135, vcc
	v_add_co_u32_e32 v140, vcc, s47, v134
	global_load_dword v139, v[138:139], off
	s_nop 0
	v_addc_co_u32_e32 v141, vcc, 0, v135, vcc
	global_load_dword v138, v[140:141], off offset:3072
	v_add_co_u32_e32 v140, vcc, s12, v134
	s_mov_b32 s12, 0xd000
	s_nop 0
	v_addc_co_u32_e32 v141, vcc, 0, v135, vcc
	v_add_co_u32_e32 v134, vcc, s12, v134
	global_load_dword v140, v[140:141], off offset:1024
	s_nop 0
	v_addc_co_u32_e32 v135, vcc, 0, v135, vcc
	global_load_dword v141, v[134:135], off offset:3072
	v_readlane_b32 s100, v252, 7
	s_add_i32 s100, s14, s100
	s_cmpk_lt_i32 s100, 0xb0
	s_cbranch_scc0 .Lpf_none_up
	s_and_b32 vcc_lo, s100, 7
	s_or_b32 vcc_lo, vcc_lo, s16
	s_lshl_b32 vcc_lo, vcc_lo, 8
	v_add_u32_e32 v238, vcc_lo, v175
	v_ashrrev_i32_e32 v239, 31, v238
	v_lshlrev_b64 v[238:239], 11, v[238:239]
	v_lshl_add_u64 v[238:239], v[156:157], 0, v[238:239]
	s_lshl_b32 vcc_lo, s100, 5
	s_and_b32 vcc_lo, vcc_lo, 0xffffff00
	v_add_u32_e32 v240, vcc_lo, v175
	v_ashrrev_i32_e32 v241, 31, v240
	v_lshlrev_b64 v[240:241], 11, v[240:241]
	v_lshl_add_u64 v[240:241], v[158:159], 0, v[240:241]
	v_readfirstlane_b32 s100, v180
	s_mov_b32 m0, s100
	s_nop 0
	global_load_lds_dwordx4 v[238:239], off
	v_lshl_add_u64 v[242:243], v[238:239], 0, s[34:35]
	s_add_i32 m0, s100, 0x2000
	s_nop 0
	global_load_lds_dwordx4 v[242:243], off
	s_add_i32 m0, s100, 0x4000
	s_nop 0
	global_load_lds_dwordx4 v[240:241], off
	v_lshl_add_u64 v[242:243], v[240:241], 0, s[34:35]
	s_add_i32 m0, s100, 0x6000
	s_nop 0
	global_load_lds_dwordx4 v[242:243], off
	v_lshl_add_u64 v[242:243], v[238:239], 0, 64
	s_add_i32 m0, s100, 0x8000
	s_nop 0
	global_load_lds_dwordx4 v[242:243], off
	s_mov_b64 vcc, 0x40040
	v_lshl_add_u64 v[242:243], v[238:239], 0, vcc
	s_add_i32 m0, s100, 0xa000
	s_nop 0
	global_load_lds_dwordx4 v[242:243], off
	v_lshl_add_u64 v[242:243], v[240:241], 0, 64
	s_add_i32 m0, s100, 0xc000
	s_nop 0
	global_load_lds_dwordx4 v[242:243], off
	s_mov_b64 vcc, 0x40040
	v_lshl_add_u64 v[242:243], v[240:241], 0, vcc
	s_add_i32 m0, s100, 0xe000
	s_nop 0
	global_load_lds_dwordx4 v[242:243], off
	s_mov_b64 vcc, 0x80
	v_lshl_add_u64 v[242:243], v[238:239], 0, vcc
	s_add_i32 m0, s100, 0x10000
	s_nop 0
	global_load_lds_dwordx4 v[242:243], off
	s_mov_b64 vcc, 0x40080
	v_lshl_add_u64 v[242:243], v[238:239], 0, vcc
	s_add_i32 m0, s100, 0x12000
	s_nop 0
	global_load_lds_dwordx4 v[242:243], off
	s_mov_b64 vcc, 0x80
	v_lshl_add_u64 v[242:243], v[240:241], 0, vcc
	s_add_i32 m0, s100, 0x14000
	s_nop 0
	global_load_lds_dwordx4 v[242:243], off
	s_mov_b64 vcc, 0x40080
	v_lshl_add_u64 v[242:243], v[240:241], 0, vcc
	s_add_i32 m0, s100, 0x16000
	s_nop 0
	global_load_lds_dwordx4 v[242:243], off
	s_mov_b32 s101, 1
	s_branch .Lpf_done_up
.Lpf_none_up:
	global_load_dword v238, v[134:135], off offset:3072
	global_load_dword v238, v[134:135], off offset:3072
	global_load_dword v238, v[134:135], off offset:3072
	global_load_dword v238, v[134:135], off offset:3072
	global_load_dword v238, v[134:135], off offset:3072
	global_load_dword v238, v[134:135], off offset:3072
	global_load_dword v238, v[134:135], off offset:3072
	global_load_dword v238, v[134:135], off offset:3072
	global_load_dword v238, v[134:135], off offset:3072
	global_load_dword v238, v[134:135], off offset:3072
	global_load_dword v238, v[134:135], off offset:3072
	global_load_dword v238, v[134:135], off offset:3072
.Lpf_done_up:
	v_mov_b64_e32 v[134:135], s[8:9]
	v_mad_i64_i32 v[134:135], s[12:13], v133, s13, v[134:135]
	v_ashrrev_i32_e32 v133, 31, v132
	v_lshl_add_u64 v[132:133], v[132:133], 1, v[134:135]
	v_lshl_add_u64 v[132:133], v[132:133], 0, v[128:129]
	s_and_saveexec_b64 s[12:13], s[2:3]
	s_xor_b64 s[12:13], exec, s[12:13]
	s_cbranch_execz .LBB0_2343
	v_add_co_u32_e32 v134, vcc, 0x5000, v132
	v_cvt_pk_bf16_f32 v143, v30, s0
	s_nop 0
	v_addc_co_u32_e32 v135, vcc, 0, v133, vcc
	global_store_short v[134:135], v143, off offset:2048
	v_cvt_pk_bf16_f32 v143, v14, s0
	global_store_short v[134:135], v143, off offset:2112
	v_add_co_u32_e32 v134, vcc, 0x8000, v132
	v_cvt_pk_bf16_f32 v143, v31, s0
	s_nop 0
	v_addc_co_u32_e32 v135, vcc, 0, v133, vcc
	global_store_short v[134:135], v143, off offset:1024
